# attention K LDS tile: row bit3 folded into swizzle (conflict-free ds_read_b128 K fragments); all QK K-fragment reads issued up front; fewer s_waitcnt/s_nop
# speedup vs baseline: 1.0094x; 1.0094x over previous
; __device__ __forceinline__ int tid_l() { int t = threadIdx.x; asm volatile("" : "+v"(t)); return t; }
; __device__ __forceinline__ int v_st(int k, int c) { const int kk = (k & ~0xC) | ((k & 4) << 1) | ((k & 8) >> 1); return ((kk >> 3) * 4 + (c >> 5)) * 512 + ((kk & 7) * 32 + (c & 31)) * 2; }
; __device__ __forceinline__ int v_rd_base(int lane) { return ((lane & 3) << 3) | (((lane >> 2) & 3) << 6) | (((lane >> 4) & 1) << 5) | (((lane >> 5) & 1) << 8); }
; #define SLOAD_A(k0) do { vs0a = *reinterpret_cast<const bf16x8*>(&Vh[(long)((k0) + sr) * LDK + sc]); vs1a = *reinterpret_cast<const bf16x8*>(&Vh[(long)((k0) + 32 + sr) * LDK + sc]); KLOAD(ks0a, ks1a, k0); } while (0)
; #define SLOAD_B(k0) do { vs0b = *reinterpret_cast<const bf16x8*>(&Vh[(long)((k0) + sr) * LDK + sc]); vs1b = *reinterpret_cast<const bf16x8*>(&Vh[(long)((k0) + 32 + sr) * LDK + sc]); KLOAD(ks0b, ks1b, k0); } while (0)
; template <int ND0, int LDQ, int LDK, int LDO> ...
;   const int tid = tid_l(), wid = tid >> 6, lane = tid & 63, r32 = lane & 31, hi = lane >> 5;
;   char* V_lds = lds; char* K_lds = lds + 2 * SHM_V;
;   float* ws = (float*)(lds + 2 * SHM_V + 2 * SHM_K) + wid * 64; float* li_l = ws; float* al_l = ws + 32;
;   constexpr bool PRE = true;
;   float m_reg = PRE ? 0.f : -1e30f, l_reg = 0; f32x16 o[4] = {}; bf16x8 qr[ND0];
;   const bf16_t* Qw = Qb + (long)(wid * QBLK + r32) * LDQ + hi * 8;
; #pragma unroll
;   for (int d0 = 0; d0 < ND0; ++d0) qr[d0] = *reinterpret_cast<const bf16x8*>(Qw + d0 * 16);
;   const int sr = tid >> 4, sc = (tid & 15) * 8, vst0 = v_st(sr, sc), vst1 = v_st(32 + sr, sc);
;   const int vb0 = (int)(uintptr_t)V_lds + v_rd_base(lane);
;   bf16x8 vs0a, vs1a, ks0a, ks1a = {}, vs0b, vs1b, ks0b, ks1b = {};
;   const int kr = tid >> 3, kcb = kofs + (tid & 7) * 16;
;     ...
;   f32x16 pA0, pA1, pB0, pB1; float mnA, mnB, alA, alB; bf16x8 pa0, pa1, pa2, pa3; const int NT = seq / KVBLK;
;   const char* Kq0 = K_lds + kofs; const char* Kq1 = K_lds + SHM_K + kofs;
;   if (ND0 == 4 && have_pf) { vs0a = pfv0; vs1a = pfv1; ks0a = pfk0; } else { SLOAD_A(0); }
;   asm volatile("s_waitcnt vmcnt(0)" ::: "memory"); SWRITE_A(0); __syncthreads();
;   qkt<ND0>(pA0, pA1, Kq0, qr, r32, hi); PSM(pA0, pA1, mnA, alA);
;   SLOAD_B(KVBLK); if (2 < NT) SLOAD_A(2 * KVBLK);
;   SWAIT(); SWRITE_B(1); __syncthreads();
.LBB0_143:
	s_mul_i32 s8, s3, 0xc00
	s_mul_hi_u32 s9, s2, 0xc00
	s_add_i32 s9, s9, s8
	s_mul_i32 s8, s2, 0xc00
	s_add_u32 s8, s60, s8
	s_addc_u32 s9, s61, s9
	s_lshl_b32 s16, s37, 8
	s_add_u32 s8, s8, s16
	s_mul_i32 s5, s5, 0xcc0000
	s_mul_hi_u32 s16, s4, 0xcc0000
	s_addc_u32 s9, s9, 0
	s_add_i32 s16, s16, s5
	s_mul_i32 s17, s4, 0xcc0000
	s_add_u32 s4, s60, s17
	s_waitcnt vmcnt(0)
	v_mov_b32_e32 v16, v228
	s_addc_u32 s5, s61, s16
	s_lshl_b32 s39, s34, 8
	s_add_u32 s4, s4, s39
	v_ashrrev_i32_e32 v17, 4, v16
	v_lshlrev_b32_e32 v19, 3, v16
	v_add_u32_e32 v22, 32, v17
	s_movk_i32 s39, 0x600
	v_and_b32_e32 v18, 0x78, v19
	s_waitcnt lgkmcnt(1)
	v_mad_i64_i32 v[0:1], s[40:41], v17, s39, 0
	v_mad_i64_i32 v[4:5], s[40:41], v22, s39, 0
	s_addc_u32 s5, s5, 0
	v_or_b32_e32 v0, v0, v18
	v_or_b32_e32 v4, v4, v18
	v_lshl_add_u64 v[8:9], v[0:1], 1, s[4:5]
	v_lshl_add_u64 v[12:13], v[4:5], 1, s[4:5]
	s_waitcnt lgkmcnt(0)
	global_load_dwordx4 v[0:3], v[8:9], off offset:2560
	global_load_dwordx4 v[4:7], v[12:13], off offset:2560
	s_nop 0
	global_load_dwordx4 v[8:11], v[8:9], off offset:2048
	s_nop 0
	global_load_dwordx4 v[12:15], v[12:13], off offset:2048
	v_ashrrev_i32_e32 v181, 6, v16
	v_and_b32_e32 v179, 31, v16
	v_lshlrev_b32_e32 v184, 5, v181
	v_bfe_u32 v183, v16, 5, 1
	v_or_b32_e32 v23, v184, v179
	v_mov_b64_e32 v[20:21], s[8:9]
	s_movk_i32 s8, 0xc00
	v_mad_i64_i32 v[20:21], s[8:9], v23, s8, v[20:21]
	v_lshlrev_b32_e32 v112, 4, v183
	v_lshl_add_u64 v[20:21], v[20:21], 0, v[112:113]
	global_load_dwordx4 v[114:117], v[20:21], off
	global_load_dwordx4 v[122:125], v[20:21], off offset:32
	global_load_dwordx4 v[142:145], v[20:21], off offset:64
	global_load_dwordx4 v[138:141], v[20:21], off offset:96
	global_load_dwordx4 v[134:137], v[20:21], off offset:128
	global_load_dwordx4 v[130:133], v[20:21], off offset:160
	global_load_dwordx4 v[126:129], v[20:21], off offset:192
	global_load_dwordx4 v[118:121], v[20:21], off offset:224
	v_and_b32_e32 v24, 0xfffff0, v17
	v_lshlrev_b32_e32 v25, 1, v17
	v_lshrrev_b32_e32 v26, 1, v17
	v_and_b32_e32 v27, 3, v17
	v_and_or_b32 v24, v25, 8, v24
	v_and_or_b32 v25, v26, 4, v27
	v_and_b32_e32 v26, 0xfffff0, v22
	v_lshlrev_b32_e32 v27, 1, v22
	v_and_b32_e32 v23, 0xf0, v16
	v_bfe_u32 v19, v19, 5, 2
	v_lshlrev_b32_e32 v28, 8, v17
	v_lshlrev_b32_e32 v186, 1, v18
	v_lshlrev_b32_e32 v22, 8, v22
	v_lshrrev_b32_e32 v24, 1, v24
	v_and_or_b32 v26, v27, 8, v26
	v_bitop3_b32 v27, v186, v28, v23 bitop3:0xde
	v_bitop3_b32 v22, v186, v22, v23 bitop3:0xde
	v_or_b32_e32 v23, v24, v19
	v_lshrrev_b32_e32 v24, 1, v26
	v_lshlrev_b32_e32 v25, 6, v25
	v_and_b32_e32 v29, 48, v186
	v_add_u32_e32 v196, 0, v22
	v_lshlrev_b32_e32 v22, 9, v23
	v_or_b32_e32 v19, v24, v19
	v_or3_b32 v22, v22, v25, v29
	v_lshlrev_b32_e32 v19, 9, v19
	v_or3_b32 v19, v19, v25, v29
	v_add_u32_e32 v197, 0, v22
	v_add_u32_e32 v195, 0, v27
	v_add_u32_e32 v198, 0, v19
	s_waitcnt vmcnt(0)
	v_lshlrev_b32_e32 v19, 8, v179
	v_or_b32_e32 v25, 64, v112
	s_waitcnt vmcnt(11)
	ds_write_b128 v197, v[0:3]
	s_waitcnt vmcnt(10)
	ds_write_b128 v198, v[4:7]
	s_waitcnt vmcnt(9)
	ds_write_b128 v195, v[8:11] offset:32768
	s_waitcnt vmcnt(8)
	ds_write_b128 v196, v[12:15] offset:32768
	v_lshlrev_b32_e32 v0, 4, v16
	v_and_b32_e32 v24, 0xf0, v0
	v_bitop3_b32 v0, v112, v19, v24 bitop3:0xde
	v_add_u32_e32 v199, 0, v0
	s_waitcnt lgkmcnt(0)
	s_barrier
	ds_read_b128 v[0:3], v199 offset:32768
	ds_read_b128 v[20:23], v199 offset:40960
	s_waitcnt vmcnt(7) lgkmcnt(0)
	v_mfma_f32_32x32x16_bf16 v[64:79], v[20:23], v[114:117], 0
	v_or_b32_e32 v20, 32, v112
	v_bitop3_b32 v20, v20, v19, v24 bitop3:0xde
	v_add_u32_e32 v200, 0, v20
	ds_read_b128 v[20:23], v200 offset:32768
	v_mfma_f32_32x32x16_bf16 v[0:15], v[0:3], v[114:117], 0
	s_waitcnt vmcnt(6) lgkmcnt(0)
	v_mfma_f32_32x32x16_bf16 v[0:15], v[20:23], v[122:125], v[0:15]
	ds_read_b128 v[20:23], v200 offset:40960
	s_waitcnt lgkmcnt(0)
	v_mfma_f32_32x32x16_bf16 v[64:79], v[20:23], v[122:125], v[64:79]
	v_bitop3_b32 v20, v25, v19, v24 bitop3:0xde
	v_add_u32_e32 v202, 0, v20
	ds_read_b128 v[20:23], v202 offset:32768
	v_or_b32_e32 v25, 0x60, v112
	v_bitop3_b32 v25, v25, v19, v24 bitop3:0xde
	v_add_u32_e32 v201, 0, v25
	v_or_b32_e32 v25, 0x80, v112
	s_waitcnt vmcnt(5) lgkmcnt(0)
	v_mfma_f32_32x32x16_bf16 v[0:15], v[20:23], v[142:145], v[0:15]
	ds_read_b128 v[20:23], v202 offset:40960
	v_bitop3_b32 v25, v25, v19, v24 bitop3:0xde
	v_add_u32_e32 v203, 0, v25
	v_or_b32_e32 v25, 0xa0, v112
	v_bitop3_b32 v25, v25, v19, v24 bitop3:0xde
	v_add_u32_e32 v204, 0, v25
	v_or_b32_e32 v25, 0xc0, v112
	s_waitcnt lgkmcnt(0)
	v_mfma_f32_32x32x16_bf16 v[64:79], v[20:23], v[142:145], v[64:79]
	ds_read_b128 v[20:23], v201 offset:32768
	v_bitop3_b32 v25, v25, v19, v24 bitop3:0xde
	v_add_u32_e32 v206, 0, v25
	v_or_b32_e32 v25, 0xe0, v112
	v_bitop3_b32 v19, v25, v19, v24 bitop3:0xde
	v_add_u32_e32 v205, 0, v19
	s_waitcnt vmcnt(4) lgkmcnt(0)
	v_mfma_f32_32x32x16_bf16 v[0:15], v[20:23], v[138:141], v[0:15]
	ds_read_b128 v[20:23], v201 offset:40960
	s_waitcnt lgkmcnt(0)
	v_mfma_f32_32x32x16_bf16 v[64:79], v[20:23], v[138:141], v[64:79]
	ds_read_b128 v[20:23], v203 offset:32768
	s_waitcnt vmcnt(3) lgkmcnt(0)
	v_mfma_f32_32x32x16_bf16 v[0:15], v[20:23], v[134:137], v[0:15]
	ds_read_b128 v[20:23], v203 offset:40960
	s_waitcnt lgkmcnt(0)
	v_mfma_f32_32x32x16_bf16 v[64:79], v[20:23], v[134:137], v[64:79]
	ds_read_b128 v[20:23], v204 offset:32768
	s_waitcnt vmcnt(2) lgkmcnt(0)
	v_mfma_f32_32x32x16_bf16 v[0:15], v[20:23], v[130:133], v[0:15]
	ds_read_b128 v[20:23], v204 offset:40960
	s_waitcnt lgkmcnt(0)
	v_mfma_f32_32x32x16_bf16 v[64:79], v[20:23], v[130:133], v[64:79]
	ds_read_b128 v[20:23], v206 offset:32768
	s_waitcnt vmcnt(1) lgkmcnt(0)
	v_mfma_f32_32x32x16_bf16 v[0:15], v[20:23], v[126:129], v[0:15]
	ds_read_b128 v[20:23], v206 offset:40960
	s_waitcnt lgkmcnt(0)
	v_mfma_f32_32x32x16_bf16 v[64:79], v[20:23], v[126:129], v[64:79]
	ds_read_b128 v[20:23], v205 offset:32768
	s_waitcnt vmcnt(0) lgkmcnt(0)
	v_mfma_f32_32x32x16_bf16 v[0:15], v[20:23], v[118:121], v[0:15]
	ds_read_b128 v[20:23], v205 offset:40960
	s_waitcnt lgkmcnt(0)
	v_mfma_f32_32x32x16_bf16 v[64:79], v[20:23], v[118:121], v[64:79]
	s_nop 8
	v_max_f32_e32 v19, v1, v1
	v_max_f32_e32 v20, v0, v0
	v_max_f32_e32 v19, v20, v19
	v_max3_f32 v19, v19, v2, v3
	v_max3_f32 v19, v19, v4, v5
	v_max3_f32 v19, v19, v6, v7
	v_max3_f32 v19, v19, v8, v9
	v_max3_f32 v19, v19, v10, v11
	v_max3_f32 v19, v19, v12, v13
	v_max3_f32 v19, v19, v14, v15
	v_max3_f32 v19, v19, v64, v65
	v_max3_f32 v19, v19, v66, v67
	v_max3_f32 v19, v19, v68, v69
	v_max3_f32 v19, v19, v70, v71
	v_max3_f32 v19, v19, v72, v73
	v_max3_f32 v19, v19, v74, v75
	v_max3_f32 v19, v19, v76, v77
	v_max3_f32 v19, v19, v78, v79
	v_mov_b32_e32 v20, v19
	s_nop 1
	v_permlane32_swap_b32_e32 v19, v20
	v_max_f32_e32 v20, v20, v20
	v_max_f32_e32 v19, v19, v19
	v_max_f32_e32 v19, v19, v20
	v_cmp_ge_f32_e32 vcc, s45, v19
	s_cmp_eq_u64 vcc, exec
	s_cbranch_scc0 .LBB0_175
	v_mov_b32_e32 v207, 1.0
	v_mov_b32_e32 v193, 0

; #define SBAR() __builtin_amdgcn_sched_barrier(0)
; #define KWRITE(b, src0, src1) do { if constexpr (ND0 == 4) { *(bf16x8*)(K_lds + (b) * SHM_K + KSWZ(kr, kcb)) = src0; } \
;     else { int kc = sc * 2; *(bf16x8*)(K_lds + (b) * SHM_K + KSWZ(sr, kc)) = src0; *(bf16x8*)(K_lds + (b) * SHM_K + KSWZ(32 + sr, kc)) = src1; } } while (0)
; #define SLOAD_B(k0) do { vs0b = *reinterpret_cast<const bf16x8*>(&Vh[(long)((k0) + sr) * LDK + sc]); vs1b = *reinterpret_cast<const bf16x8*>(&Vh[(long)((k0) + 32 + sr) * LDK + sc]); KLOAD(ks0b, ks1b, k0); } while (0)
; #define PSM(P0, P1, MN, AL) do { if constexpr (PRE) partialSM_pre(P0, P1, m_reg, AL, 11.541560327111707f); else partialSM(P0, P1, m_reg, MN, AL, C, thr_raw); } while (0)
; __device__ __forceinline__ void finishSM(f32x16& p0, f32x16& p1, float alpha, float& l_reg, bf16x8& pa0, bf16x8& pa1, bf16x8& pa2, bf16x8& pa3) {
; #pragma unroll
;   for (int r = 0; r < 16; ++r) p1[r] = __builtin_amdgcn_exp2f(p1[r]);
;   float ps = 0;
; #pragma unroll
;   for (int r = 0; r < 16; ++r) ps += p0[r];
; #pragma unroll
;   for (int r = 0; r < 16; ++r) ps += p1[r];
;   { auto rr = __builtin_amdgcn_permlane32_swap(__float_as_uint(ps), __float_as_uint(ps), false, false);
;     ps = __uint_as_float(rr[0]) + __uint_as_float(rr[1]); }
;   l_reg = l_reg * alpha + ps;
;     ...
;   PK4(p0, 0, pa0); PK4(p0, 8, pa1); PK4(p1, 0, pa2); PK4(p1, 8, pa3);
;     ...
; }
; template <int ND0>
; __device__ __forceinline__ void qkt(f32x16& p0, f32x16& p1, const char* Ks, const bf16x8* qr, int r32, int hi) {
;   p0 = f32x16{}; p1 = f32x16{};
; #pragma unroll
;   for (int d0 = 0; d0 < ND0; ++d0) { int cb = (d0 * 16 + hi * 8) * 2;
;     bf16x8 b0 = *reinterpret_cast<const bf16x8*>(Ks + KSWZ(r32, cb));
;     bf16x8 b1 = *reinterpret_cast<const bf16x8*>(Ks + KSWZ(32 + r32, cb));
;     p0 = __builtin_amdgcn_mfma_f32_32x32x16_bf16(b0, qr[d0], p0, 0, 0, 0);
;     p1 = __builtin_amdgcn_mfma_f32_32x32x16_bf16(b1, qr[d0], p1, 0, 0, 0); }
; }
; template <int ND0, int LDQ, int LDK, int LDO> ...
;     ...
;   for (int j = 1; j + 1 < NT; j += 2) {
;     SBAR(); qkt<ND0>(pB0, pB1, Kq1, qr, r32, hi);
;     finishSM(pA0, pA1, alA, l_reg, pa0, pa1, pa2, pa3); SBAR();
;     SLOAD_B((j + 2) * KVBLK); SBAR();
;     pv_d0(o, vb0, pa0, pa1, pa2, pa3); KWRITE(0, ks0a, ks1a); PSM(pB0, pB1, mnB, alB);
.LBB0_146:
	ds_read_b128 v[208:211], v200 offset:49152
	ds_read_b128 v[214:217], v200 offset:57344
	v_exp_f32_e32 v170, v64
	v_add_f32_e32 v64, 0, v176
	s_waitcnt lgkmcnt(2)
	v_mfma_f32_32x32x16_bf16 v[96:111], v[80:83], v[114:117], 0
	v_add_f32_e32 v64, v213, v64
	v_add_f32_e32 v64, v174, v64
	v_add_f32_e32 v64, v177, v64
	v_add_f32_e32 v64, v173, v64
	v_add_f32_e32 v64, v175, v64
	v_add_f32_e32 v64, v171, v64
	v_add_f32_e32 v64, v172, v64
	v_mfma_f32_32x32x16_bf16 v[80:95], v[84:87], v[114:117], 0
	v_add_f32_e32 v64, v167, v64
	v_add_f32_e32 v64, v169, v64
	v_add_f32_e32 v64, v166, v64
	v_add_f32_e32 v64, v168, v64
	v_add_f32_e32 v64, v163, v64
	v_add_f32_e32 v64, v165, v64
	v_add_f32_e32 v64, v162, v64
	s_waitcnt lgkmcnt(0)
	v_mfma_f32_32x32x16_bf16 v[96:111], v[208:211], v[122:125], v[96:111]
	v_exp_f32_e32 v212, v67
	v_add_f32_e32 v64, v164, v64
	v_add_f32_e32 v64, v170, v64
	v_exp_f32_e32 v218, v72
	v_exp_f32_e32 v219, v73
	v_exp_f32_e32 v220, v74
	v_exp_f32_e32 v221, v75
	v_mfma_f32_32x32x16_bf16 v[80:95], v[214:217], v[122:125], v[80:95]
	ds_read_b128 v[208:211], v202 offset:49152
	ds_read_b128 v[214:217], v202 offset:57344
	v_exp_f32_e32 v222, v76
	v_exp_f32_e32 v223, v77
	v_exp_f32_e32 v224, v78
	v_exp_f32_e32 v79, v79
	s_waitcnt lgkmcnt(0)
	v_mfma_f32_32x32x16_bf16 v[96:111], v[208:211], v[142:145], v[96:111]
	v_mfma_f32_32x32x16_bf16 v[80:95], v[214:217], v[142:145], v[80:95]
	ds_read_b128 v[208:211], v201 offset:49152
	ds_read_b128 v[214:217], v201 offset:57344
	s_waitcnt lgkmcnt(0)
	v_mfma_f32_32x32x16_bf16 v[96:111], v[208:211], v[138:141], v[96:111]
	v_mfma_f32_32x32x16_bf16 v[80:95], v[214:217], v[138:141], v[80:95]
	ds_read_b128 v[208:211], v203 offset:49152
	ds_read_b128 v[214:217], v203 offset:57344
	s_waitcnt lgkmcnt(0)
	v_mfma_f32_32x32x16_bf16 v[96:111], v[208:211], v[134:137], v[96:111]
	v_mfma_f32_32x32x16_bf16 v[80:95], v[214:217], v[134:137], v[80:95]
	ds_read_b128 v[208:211], v204 offset:49152
	ds_read_b128 v[214:217], v204 offset:57344
	s_waitcnt lgkmcnt(0)
	v_mfma_f32_32x32x16_bf16 v[96:111], v[208:211], v[130:133], v[96:111]
	v_mfma_f32_32x32x16_bf16 v[80:95], v[214:217], v[130:133], v[80:95]
	ds_read_b128 v[208:211], v206 offset:49152
	ds_read_b128 v[214:217], v206 offset:57344
	s_waitcnt lgkmcnt(0)
	v_mfma_f32_32x32x16_bf16 v[96:111], v[208:211], v[126:129], v[96:111]
	v_mfma_f32_32x32x16_bf16 v[80:95], v[214:217], v[126:129], v[80:95]
	ds_read_b128 v[208:211], v205 offset:49152
	ds_read_b128 v[214:217], v205 offset:57344
	s_waitcnt lgkmcnt(0)
	v_mfma_f32_32x32x16_bf16 v[96:111], v[208:211], v[118:121], v[96:111]
	v_exp_f32_e32 v210, v65
	v_exp_f32_e32 v211, v66
	v_add_f32_e32 v64, v210, v64
	v_add_f32_e32 v64, v211, v64
	v_add_f32_e32 v64, v212, v64
	v_mfma_f32_32x32x16_bf16 v[80:95], v[214:217], v[118:121], v[80:95]
	v_exp_f32_e32 v214, v68
	v_exp_f32_e32 v215, v69
	v_exp_f32_e32 v216, v70
	v_exp_f32_e32 v217, v71
	v_add_f32_e32 v64, v214, v64
	v_add_f32_e32 v64, v215, v64
	v_add_f32_e32 v64, v216, v64
	v_add_f32_e32 v64, v217, v64
	v_add_f32_e32 v64, v218, v64
	v_add_f32_e32 v64, v219, v64
	v_add_f32_e32 v64, v220, v64
	v_add_f32_e32 v64, v221, v64
	v_add_f32_e32 v64, v222, v64
	v_add_f32_e32 v64, v223, v64
	v_add_f32_e32 v64, v224, v64
	v_add_f32_e32 v208, v79, v64
	v_mov_b32_e32 v209, v208
	v_cvt_pk_bf16_f32 v64, v176, v213
	v_cvt_pk_bf16_f32 v65, v174, v177
	v_cvt_pk_bf16_f32 v66, v173, v175
	v_cvt_pk_bf16_f32 v67, v171, v172
	v_cvt_pk_bf16_f32 v68, v167, v169
	v_cvt_pk_bf16_f32 v69, v166, v168
	v_cvt_pk_bf16_f32 v70, v163, v165
	v_cvt_pk_bf16_f32 v71, v162, v164
	v_cvt_pk_bf16_f32 v72, v170, v210
	v_cvt_pk_bf16_f32 v73, v211, v212
	v_cvt_pk_bf16_f32 v74, v214, v215
	v_cvt_pk_bf16_f32 v75, v216, v217
	v_cvt_pk_bf16_f32 v76, v218, v219
	v_cvt_pk_bf16_f32 v77, v220, v221
	v_cvt_pk_bf16_f32 v78, v222, v223
	v_cvt_pk_bf16_f32 v79, v224, v79
	v_permlane32_swap_b32_e32 v208, v209
	v_permlane32_swap_b32_e32 v64, v66
	v_permlane32_swap_b32_e32 v65, v67
	v_permlane32_swap_b32_e32 v68, v70
	v_permlane32_swap_b32_e32 v69, v71
	v_permlane32_swap_b32_e32 v72, v74
	v_permlane32_swap_b32_e32 v73, v75
	v_permlane32_swap_b32_e32 v76, v78
	v_permlane32_swap_b32_e32 v77, v79
	s_mov_b32 s4, 0xfffb8000
	v_add_co_u32_e32 v166, vcc, s4, v188
	s_mov_b32 s4, 0xfffd0000
	s_nop 0
	v_addc_co_u32_e32 v167, vcc, -1, v189, vcc
	v_add_co_u32_e32 v174, vcc, s4, v188
	s_nop 1
	v_addc_co_u32_e32 v175, vcc, -1, v189, vcc
	global_load_dwordx4 v[162:165], v[166:167], off
	global_load_dwordx4 v[170:173], v[166:167], off offset:-512
	global_load_dwordx4 v[166:169], v[174:175], off
	global_load_dwordx4 v[174:177], v[174:175], off offset:-512
	v_cmp_neq_f32_e32 vcc, 0, v193
	ds_read_b64_tr_b16 v[210:211], v194 offset:0
	ds_read_b64_tr_b16 v[212:213], v194 offset:0x800
	ds_read_b64_tr_b16 v[214:215], v194 offset:0x1000
	ds_read_b64_tr_b16 v[216:217], v194 offset:0x1800
	ds_read_b64_tr_b16 v[218:219], v194 offset:0x2000
	ds_read_b64_tr_b16 v[220:221], v194 offset:0x2800
	ds_read_b64_tr_b16 v[222:223], v194 offset:0x3000
	ds_read_b64_tr_b16 v[224:225], v194 offset:0x3800
	s_cbranch_vccnz .LBB0_163
; #define SBAR() __builtin_amdgcn_sched_barrier(0)
; __device__ __forceinline__ void partialSM_pre(f32x16& p0, f32x16& p1, float& m_ref, float& alpha, const float thr2) {
;     ...
;   float pmax = p0[0];
; #pragma unroll
;   for (int r = 1; r < 16; ++r) pmax = fmaxf(pmax, p0[r]);
; #pragma unroll
;   for (int r = 0; r < 16; ++r) pmax = fmaxf(pmax, p1[r]);
;   { auto rr = __builtin_amdgcn_permlane32_swap(__float_as_uint(pmax), __float_as_uint(pmax), false, false);
;     pmax = fmaxf(__uint_as_float(rr[0]), __uint_as_float(rr[1])); }
;   if (__builtin_expect(__all(pmax <= thr2), 1)) { alpha = 1.f; }
; template <int OFF> __device__ __forceinline__ s16x4 tr_read(int vb) {
;   s16x4 r; asm volatile("ds_read_b64_tr_b16 %0, %1 offset:%2" : "=&v"(r) : "v"(vb), "i"(OFF) : "memory"); return r;
; }
; template <int D0> __device__ __forceinline__ void pv_one(f32x16& od, int vb, bf16x8 pa0, bf16x8 pa1, bf16x8 pa2, bf16x8 pa3) {
;   const s16x4 l0 = tr_read<v_rd_off(D0, 0, 0)>(vb), h0 = tr_read<v_rd_off(D0, 0, 1)>(vb), l1 = tr_read<v_rd_off(D0, 1, 0)>(vb), h1 = tr_read<v_rd_off(D0, 1, 1)>(vb);
;   const s16x4 l2 = tr_read<v_rd_off(D0, 2, 0)>(vb), h2 = tr_read<v_rd_off(D0, 2, 1)>(vb), l3 = tr_read<v_rd_off(D0, 3, 0)>(vb), h3 = tr_read<v_rd_off(D0, 3, 1)>(vb);
;   asm volatile("s_waitcnt lgkmcnt(0)" ::: "memory"); SBAR();
;     ...
;   od = __builtin_amdgcn_mfma_f32_32x32x16_bf16(pa0, PK(l0, h0), od, 0, 0, 0);
;   od = __builtin_amdgcn_mfma_f32_32x32x16_bf16(pa1, PK(l1, h1), od, 0, 0, 0);
;   od = __builtin_amdgcn_mfma_f32_32x32x16_bf16(pa2, PK(l2, h2), od, 0, 0, 0);
;   od = __builtin_amdgcn_mfma_f32_32x32x16_bf16(pa3, PK(l3, h3), od, 0, 0, 0);
;     ...
; }
; __device__ __forceinline__ void pv_d0(f32x16* o, int vb, bf16x8 pa0, bf16x8 pa1, bf16x8 pa2, bf16x8 pa3) {
;   pv_one<0>(o[0], vb, pa0, pa1, pa2, pa3); pv_one<1>(o[1], vb, pa0, pa1, pa2, pa3); pv_one<2>(o[2], vb, pa0, pa1, pa2, pa3); pv_one<3>(o[3], vb, pa0, pa1, pa2, pa3);
; }
.LBB0_147:
	v_max_f32_e32 v180, v97, v97
	v_max_f32_e32 v182, v96, v96
	v_max_f32_e32 v180, v182, v180
	v_max3_f32 v180, v180, v98, v99
	v_max3_f32 v180, v180, v100, v101
	v_max3_f32 v180, v180, v102, v103
	v_max3_f32 v180, v180, v104, v105
	v_max3_f32 v180, v180, v106, v107
	v_max3_f32 v180, v180, v108, v109
	v_max3_f32 v180, v180, v110, v111
	v_max3_f32 v180, v180, v80, v81
	v_max3_f32 v180, v180, v82, v83
	v_max3_f32 v180, v180, v84, v85
	v_max3_f32 v180, v180, v86, v87
	v_max3_f32 v180, v180, v88, v89
	v_max3_f32 v180, v180, v90, v91
	v_max3_f32 v180, v180, v92, v93
	v_max3_f32 v180, v180, v94, v95
	v_mov_b32_e32 v182, v180
	s_nop 1
	v_permlane32_swap_b32_e32 v180, v182
	v_max_f32_e32 v182, v182, v182
	v_max_f32_e32 v180, v180, v180
	v_max_f32_e32 v180, v180, v182
	s_waitcnt lgkmcnt(4)
	v_mfma_f32_32x32x16_bf16 v[0:15], v[64:67], v[210:213], v[0:15]
	ds_read_b64_tr_b16 v[210:211], v194 offset:0x200
	ds_read_b64_tr_b16 v[212:213], v194 offset:0xa00
	v_mfma_f32_32x32x16_bf16 v[0:15], v[68:71], v[214:217], v[0:15]
	ds_read_b64_tr_b16 v[214:215], v194 offset:0x1200
	ds_read_b64_tr_b16 v[216:217], v194 offset:0x1a00
	s_waitcnt lgkmcnt(4)
	v_mfma_f32_32x32x16_bf16 v[0:15], v[72:75], v[218:221], v[0:15]
	ds_read_b64_tr_b16 v[218:219], v194 offset:0x2200
	ds_read_b64_tr_b16 v[220:221], v194 offset:0x2a00
	v_mfma_f32_32x32x16_bf16 v[0:15], v[76:79], v[222:225], v[0:15]
	ds_read_b64_tr_b16 v[222:223], v194 offset:0x3200
	ds_read_b64_tr_b16 v[224:225], v194 offset:0x3a00
	s_waitcnt lgkmcnt(4)
	v_mfma_f32_32x32x16_bf16 v[48:63], v[64:67], v[210:213], v[48:63]
	ds_read_b64_tr_b16 v[210:211], v194 offset:0x400
	ds_read_b64_tr_b16 v[212:213], v194 offset:0xc00
	v_mfma_f32_32x32x16_bf16 v[48:63], v[68:71], v[214:217], v[48:63]
	ds_read_b64_tr_b16 v[214:215], v194 offset:0x1400
	ds_read_b64_tr_b16 v[216:217], v194 offset:0x1c00
	s_waitcnt lgkmcnt(4)
	v_mfma_f32_32x32x16_bf16 v[48:63], v[72:75], v[218:221], v[48:63]
	ds_read_b64_tr_b16 v[218:219], v194 offset:0x2400
	ds_read_b64_tr_b16 v[220:221], v194 offset:0x2c00
	v_mfma_f32_32x32x16_bf16 v[48:63], v[76:79], v[222:225], v[48:63]
	ds_read_b64_tr_b16 v[222:223], v194 offset:0x3400
	ds_read_b64_tr_b16 v[224:225], v194 offset:0x3c00
	s_waitcnt lgkmcnt(4)
	v_mfma_f32_32x32x16_bf16 v[32:47], v[64:67], v[210:213], v[32:47]
	ds_read_b64_tr_b16 v[210:211], v194 offset:0x600
	ds_read_b64_tr_b16 v[212:213], v194 offset:0xe00
	v_mfma_f32_32x32x16_bf16 v[32:47], v[68:71], v[214:217], v[32:47]
	ds_read_b64_tr_b16 v[214:215], v194 offset:0x1600
	ds_read_b64_tr_b16 v[216:217], v194 offset:0x1e00
	s_waitcnt lgkmcnt(4)
	v_mfma_f32_32x32x16_bf16 v[32:47], v[72:75], v[218:221], v[32:47]
	ds_read_b64_tr_b16 v[218:219], v194 offset:0x2600
	ds_read_b64_tr_b16 v[220:221], v194 offset:0x2e00
	v_mfma_f32_32x32x16_bf16 v[32:47], v[76:79], v[222:225], v[32:47]
	ds_read_b64_tr_b16 v[222:223], v194 offset:0x3600
	ds_read_b64_tr_b16 v[224:225], v194 offset:0x3e00
	s_waitcnt lgkmcnt(4)
	v_mfma_f32_32x32x16_bf16 v[16:31], v[64:67], v[210:213], v[16:31]
	s_waitcnt vmcnt(4)
	ds_write_b128 v195, v[150:153] offset:32768
	ds_write_b128 v196, v[146:149] offset:32768
	v_mfma_f32_32x32x16_bf16 v[16:31], v[68:71], v[214:217], v[16:31]
	s_waitcnt lgkmcnt(2)
	v_mfma_f32_32x32x16_bf16 v[16:31], v[72:75], v[218:221], v[16:31]
	v_mfma_f32_32x32x16_bf16 v[16:31], v[76:79], v[222:225], v[16:31]
	v_cmp_ge_f32_e32 vcc, s45, v180
	s_cmp_eq_u64 vcc, exec
	v_mov_b32_e32 v210, 1.0
	s_cbranch_scc0 .LBB0_164

; #define SBAR() __builtin_amdgcn_sched_barrier(0)
; #define KWRITE(b, src0, src1) do { if constexpr (ND0 == 4) { *(bf16x8*)(K_lds + (b) * SHM_K + KSWZ(kr, kcb)) = src0; } \
;     else { int kc = sc * 2; *(bf16x8*)(K_lds + (b) * SHM_K + KSWZ(sr, kc)) = src0; *(bf16x8*)(K_lds + (b) * SHM_K + KSWZ(32 + sr, kc)) = src1; } } while (0)
; #define SLOAD_A(k0) do { vs0a = *reinterpret_cast<const bf16x8*>(&Vh[(long)((k0) + sr) * LDK + sc]); vs1a = *reinterpret_cast<const bf16x8*>(&Vh[(long)((k0) + 32 + sr) * LDK + sc]); KLOAD(ks0a, ks1a, k0); } while (0)
; #define PSM(P0, P1, MN, AL) do { if constexpr (PRE) partialSM_pre(P0, P1, m_reg, AL, 11.541560327111707f); else partialSM(P0, P1, m_reg, MN, AL, C, thr_raw); } while (0)
; __device__ __forceinline__ void finishSM(f32x16& p0, f32x16& p1, float alpha, float& l_reg, bf16x8& pa0, bf16x8& pa1, bf16x8& pa2, bf16x8& pa3) {
; #pragma unroll
;   for (int r = 0; r < 16; ++r) p1[r] = __builtin_amdgcn_exp2f(p1[r]);
;   float ps = 0;
; #pragma unroll
;   for (int r = 0; r < 16; ++r) ps += p0[r];
; #pragma unroll
;   for (int r = 0; r < 16; ++r) ps += p1[r];
;   { auto rr = __builtin_amdgcn_permlane32_swap(__float_as_uint(ps), __float_as_uint(ps), false, false);
;     ps = __uint_as_float(rr[0]) + __uint_as_float(rr[1]); }
;   l_reg = l_reg * alpha + ps;
;     ...
;   PK4(p0, 0, pa0); PK4(p0, 8, pa1); PK4(p1, 0, pa2); PK4(p1, 8, pa3);
;     ...
; }
; template <int ND0>
; __device__ __forceinline__ void qkt(f32x16& p0, f32x16& p1, const char* Ks, const bf16x8* qr, int r32, int hi) {
;   p0 = f32x16{}; p1 = f32x16{};
; #pragma unroll
;   for (int d0 = 0; d0 < ND0; ++d0) { int cb = (d0 * 16 + hi * 8) * 2;
;     bf16x8 b0 = *reinterpret_cast<const bf16x8*>(Ks + KSWZ(r32, cb));
;     bf16x8 b1 = *reinterpret_cast<const bf16x8*>(Ks + KSWZ(32 + r32, cb));
;     p0 = __builtin_amdgcn_mfma_f32_32x32x16_bf16(b0, qr[d0], p0, 0, 0, 0);
;     p1 = __builtin_amdgcn_mfma_f32_32x32x16_bf16(b1, qr[d0], p1, 0, 0, 0); }
; }
; template <int ND0, int LDQ, int LDK, int LDO> ...
;     ...
;     SBAR(); qkt<ND0>(pA0, pA1, Kq0, qr, r32, hi);
;     finishSM(pB0, pB1, alB, l_reg, pa0, pa1, pa2, pa3); SBAR();
;     if (j + 3 < NT) SLOAD_A((j + 3) * KVBLK); SBAR();
;     pv_d0(o, vb0 + (int)SHM_V, pa0, pa1, pa2, pa3); KWRITE(1, ks0b, ks1b); PSM(pA0, pA1, mnA, alA);
.LBB0_153:
	v_mov_b32_e32 v242, 0x800
	ds_read_b128 v[64:67], v199 offset:32768
	ds_read_b128 v[68:71], v199 offset:40960
	ds_read_b128 v[238:241], v200 offset:32768
	ds_read_b128 v[234:237], v200 offset:40960
	v_exp_f32_e32 v245, v88
	v_exp_f32_e32 v246, v89
	s_waitcnt lgkmcnt(2)
	v_mfma_f32_32x32x16_bf16 v[96:111], v[64:67], v[114:117], 0
	v_exp_f32_e32 v247, v90
	v_exp_f32_e32 v231, v91
	v_exp_f32_e32 v243, v92
	v_exp_f32_e32 v252, v93
	v_exp_f32_e32 v253, v94
	v_exp_f32_e32 v95, v95
	v_mfma_f32_32x32x16_bf16 v[64:79], v[68:71], v[114:117], 0
	s_waitcnt lgkmcnt(0)
	v_mfma_f32_32x32x16_bf16 v[96:111], v[238:241], v[122:125], v[96:111]
	v_mfma_f32_32x32x16_bf16 v[64:79], v[234:237], v[122:125], v[64:79]
	ds_read_b128 v[234:237], v202 offset:32768
	ds_read_b128 v[238:241], v202 offset:40960
	s_waitcnt lgkmcnt(0)
	v_mfma_f32_32x32x16_bf16 v[96:111], v[234:237], v[142:145], v[96:111]
	v_mfma_f32_32x32x16_bf16 v[64:79], v[238:241], v[142:145], v[64:79]
	ds_read_b128 v[234:237], v201 offset:32768
	ds_read_b128 v[238:241], v201 offset:40960
	s_waitcnt lgkmcnt(0)
	v_mfma_f32_32x32x16_bf16 v[96:111], v[234:237], v[138:141], v[96:111]
	v_mfma_f32_32x32x16_bf16 v[64:79], v[238:241], v[138:141], v[64:79]
	ds_read_b128 v[234:237], v203 offset:32768
	ds_read_b128 v[238:241], v203 offset:40960
	s_waitcnt lgkmcnt(0)
	v_mfma_f32_32x32x16_bf16 v[96:111], v[234:237], v[134:137], v[96:111]
	v_mfma_f32_32x32x16_bf16 v[64:79], v[238:241], v[134:137], v[64:79]
	ds_read_b128 v[234:237], v204 offset:32768
	ds_read_b128 v[238:241], v204 offset:40960
	s_waitcnt lgkmcnt(0)
	v_mfma_f32_32x32x16_bf16 v[96:111], v[234:237], v[130:133], v[96:111]
	v_mfma_f32_32x32x16_bf16 v[64:79], v[238:241], v[130:133], v[64:79]
	ds_read_b128 v[234:237], v206 offset:32768
	ds_read_b128 v[238:241], v206 offset:40960
	s_waitcnt lgkmcnt(0)
	v_mfma_f32_32x32x16_bf16 v[96:111], v[234:237], v[126:129], v[96:111]
	v_mfma_f32_32x32x16_bf16 v[64:79], v[238:241], v[126:129], v[64:79]
	ds_read_b128 v[234:237], v205 offset:32768
	ds_read_b128 v[238:241], v205 offset:40960
	s_waitcnt lgkmcnt(0)
	v_mfma_f32_32x32x16_bf16 v[96:111], v[234:237], v[118:121], v[96:111]
	v_exp_f32_e32 v234, v80
	v_add_f32_e32 v80, 0, v226
	v_add_f32_e32 v80, v244, v80
	v_add_f32_e32 v80, v224, v80
	v_add_f32_e32 v80, v227, v80
	v_add_f32_e32 v80, v223, v80
	v_add_f32_e32 v80, v225, v80
	v_add_f32_e32 v80, v221, v80
	v_add_f32_e32 v80, v222, v80
	v_add_f32_e32 v80, v218, v80
	v_add_f32_e32 v80, v220, v80
	v_add_f32_e32 v80, v217, v80
	v_add_f32_e32 v80, v219, v80
	v_add_f32_e32 v80, v214, v80
	v_exp_f32_e32 v235, v81
	v_add_f32_e32 v80, v216, v80
	v_exp_f32_e32 v236, v82
	v_add_f32_e32 v80, v213, v80
	v_exp_f32_e32 v237, v83
	v_add_f32_e32 v80, v215, v80
	v_mfma_f32_32x32x16_bf16 v[64:79], v[238:241], v[118:121], v[64:79]
	v_exp_f32_e32 v238, v84
	v_add_f32_e32 v80, v234, v80
	v_exp_f32_e32 v239, v85
	v_add_f32_e32 v80, v235, v80
	v_exp_f32_e32 v240, v86
	v_add_f32_e32 v80, v236, v80
	v_exp_f32_e32 v241, v87
	v_add_f32_e32 v80, v237, v80
	v_add_f32_e32 v80, v238, v80
	v_add_f32_e32 v80, v239, v80
	v_add_f32_e32 v80, v240, v80
	v_add_f32_e32 v80, v241, v80
	v_add_f32_e32 v80, v245, v80
	v_add_f32_e32 v80, v246, v80
	v_add_f32_e32 v80, v247, v80
	v_add_f32_e32 v80, v231, v80
	v_add_f32_e32 v80, v243, v80
	v_add_f32_e32 v80, v252, v80
	v_add_f32_e32 v80, v253, v80
	v_add_f32_e32 v211, v95, v80
	v_mov_b32_e32 v212, v211
	v_cvt_pk_bf16_f32 v80, v226, v244
	v_cvt_pk_bf16_f32 v81, v224, v227
	v_cvt_pk_bf16_f32 v82, v223, v225
	v_cvt_pk_bf16_f32 v83, v221, v222
	v_cvt_pk_bf16_f32 v84, v218, v220
	v_cvt_pk_bf16_f32 v85, v217, v219
	v_cvt_pk_bf16_f32 v86, v214, v216
	v_cvt_pk_bf16_f32 v87, v213, v215
	v_cvt_pk_bf16_f32 v88, v234, v235
	v_cvt_pk_bf16_f32 v89, v236, v237
	v_cvt_pk_bf16_f32 v90, v238, v239
	v_cvt_pk_bf16_f32 v91, v240, v241
	v_cvt_pk_bf16_f32 v92, v245, v246
	v_cvt_pk_bf16_f32 v93, v247, v231
	v_cvt_pk_bf16_f32 v94, v243, v252
	v_cvt_pk_bf16_f32 v95, v253, v95
	v_permlane32_swap_b32_e32 v211, v212
	v_permlane32_swap_b32_e32 v80, v82
	v_permlane32_swap_b32_e32 v81, v83
	v_permlane32_swap_b32_e32 v84, v86
	v_permlane32_swap_b32_e32 v85, v87
	v_permlane32_swap_b32_e32 v88, v90
	v_permlane32_swap_b32_e32 v89, v91
	v_permlane32_swap_b32_e32 v92, v94
	v_permlane32_swap_b32_e32 v93, v95
	s_add_i32 s39, s39, 2
	s_cmp_ge_u32 s39, s38
	s_cselect_b64 s[4:5], -1, 0
	s_and_b64 vcc, exec, s[4:5]
	s_cbranch_vccnz .Lgqa_pf_skip
	v_add_co_u32_e32 v146, vcc, 0xfffe8000, v188
	s_nop 1
	v_addc_co_u32_e32 v147, vcc, -1, v189, vcc
	global_load_dwordx4 v[158:161], v[146:147], off
	global_load_dwordx4 v[150:153], v[146:147], off offset:-512
	global_load_dwordx4 v[154:157], v[188:189], off
	global_load_dwordx4 v[146:149], v[188:189], off offset:-512

; #define SBAR() __builtin_amdgcn_sched_barrier(0)
; __device__ __forceinline__ void partialSM_pre(f32x16& p0, f32x16& p1, float& m_ref, float& alpha, const float thr2) {
;     ...
;   float pmax = p0[0];
; #pragma unroll
;   for (int r = 1; r < 16; ++r) pmax = fmaxf(pmax, p0[r]);
; #pragma unroll
;   for (int r = 0; r < 16; ++r) pmax = fmaxf(pmax, p1[r]);
;   { auto rr = __builtin_amdgcn_permlane32_swap(__float_as_uint(pmax), __float_as_uint(pmax), false, false);
;     pmax = fmaxf(__uint_as_float(rr[0]), __uint_as_float(rr[1])); }
;   if (__builtin_expect(__all(pmax <= thr2), 1)) { alpha = 1.f; }
; template <int OFF> __device__ __forceinline__ s16x4 tr_read(int vb) {
;   s16x4 r; asm volatile("ds_read_b64_tr_b16 %0, %1 offset:%2" : "=&v"(r) : "v"(vb), "i"(OFF) : "memory"); return r;
; }
; template <int D0> __device__ __forceinline__ void pv_one(f32x16& od, int vb, bf16x8 pa0, bf16x8 pa1, bf16x8 pa2, bf16x8 pa3) {
;   const s16x4 l0 = tr_read<v_rd_off(D0, 0, 0)>(vb), h0 = tr_read<v_rd_off(D0, 0, 1)>(vb), l1 = tr_read<v_rd_off(D0, 1, 0)>(vb), h1 = tr_read<v_rd_off(D0, 1, 1)>(vb);
;   const s16x4 l2 = tr_read<v_rd_off(D0, 2, 0)>(vb), h2 = tr_read<v_rd_off(D0, 2, 1)>(vb), l3 = tr_read<v_rd_off(D0, 3, 0)>(vb), h3 = tr_read<v_rd_off(D0, 3, 1)>(vb);
;   asm volatile("s_waitcnt lgkmcnt(0)" ::: "memory"); SBAR();
;     ...
;   od = __builtin_amdgcn_mfma_f32_32x32x16_bf16(pa0, PK(l0, h0), od, 0, 0, 0);
;   od = __builtin_amdgcn_mfma_f32_32x32x16_bf16(pa1, PK(l1, h1), od, 0, 0, 0);
;   od = __builtin_amdgcn_mfma_f32_32x32x16_bf16(pa2, PK(l2, h2), od, 0, 0, 0);
;   od = __builtin_amdgcn_mfma_f32_32x32x16_bf16(pa3, PK(l3, h3), od, 0, 0, 0);
;     ...
; }
; __device__ __forceinline__ void pv_d0(f32x16* o, int vb, bf16x8 pa0, bf16x8 pa1, bf16x8 pa2, bf16x8 pa3) {
;   pv_one<0>(o[0], vb, pa0, pa1, pa2, pa3); pv_one<1>(o[1], vb, pa0, pa1, pa2, pa3); pv_one<2>(o[2], vb, pa0, pa1, pa2, pa3); pv_one<3>(o[3], vb, pa0, pa1, pa2, pa3);
; }
.LBB0_156:
	v_max_f32_e32 v180, v97, v97
	v_max_f32_e32 v182, v96, v96
	v_max_f32_e32 v180, v182, v180
	v_max3_f32 v180, v180, v98, v99
	v_max3_f32 v180, v180, v100, v101
	v_max3_f32 v180, v180, v102, v103
	v_max3_f32 v180, v180, v104, v105
	v_max3_f32 v180, v180, v106, v107
	v_max3_f32 v180, v180, v108, v109
	v_max3_f32 v180, v180, v110, v111
	v_max3_f32 v180, v180, v64, v65
	v_max3_f32 v180, v180, v66, v67
	v_max3_f32 v180, v180, v68, v69
	v_max3_f32 v180, v180, v70, v71
	v_max3_f32 v180, v180, v72, v73
	v_max3_f32 v180, v180, v74, v75
	v_max3_f32 v180, v180, v76, v77
	v_max3_f32 v180, v180, v78, v79
	v_mov_b32_e32 v182, v180
	s_nop 1
	v_permlane32_swap_b32_e32 v180, v182
	v_max_f32_e32 v182, v182, v182
	v_max_f32_e32 v180, v180, v180
	v_max_f32_e32 v180, v180, v182
	s_waitcnt lgkmcnt(4)
	v_mfma_f32_32x32x16_bf16 v[0:15], v[80:83], v[214:217], v[0:15]
	ds_read_b64_tr_b16 v[214:215], v191 offset:0x200
	ds_read_b64_tr_b16 v[216:217], v191 offset:0xa00
	v_mfma_f32_32x32x16_bf16 v[0:15], v[84:87], v[218:221], v[0:15]
	ds_read_b64_tr_b16 v[218:219], v191 offset:0x1200
	ds_read_b64_tr_b16 v[220:221], v191 offset:0x1a00
	s_waitcnt lgkmcnt(4)
	v_mfma_f32_32x32x16_bf16 v[0:15], v[88:91], v[222:225], v[0:15]
	ds_read_b64_tr_b16 v[222:223], v191 offset:0x2200
	ds_read_b64_tr_b16 v[224:225], v191 offset:0x2a00
	v_mfma_f32_32x32x16_bf16 v[0:15], v[92:95], v[234:237], v[0:15]
	ds_read_b64_tr_b16 v[234:235], v191 offset:0x3200
	ds_read_b64_tr_b16 v[236:237], v191 offset:0x3a00
	s_waitcnt lgkmcnt(4)
	v_mfma_f32_32x32x16_bf16 v[48:63], v[80:83], v[214:217], v[48:63]
	ds_read_b64_tr_b16 v[214:215], v191 offset:0x400
	ds_read_b64_tr_b16 v[216:217], v191 offset:0xc00
	v_mfma_f32_32x32x16_bf16 v[48:63], v[84:87], v[218:221], v[48:63]
	ds_read_b64_tr_b16 v[218:219], v191 offset:0x1400
	ds_read_b64_tr_b16 v[220:221], v191 offset:0x1c00
	s_waitcnt lgkmcnt(4)
	v_mfma_f32_32x32x16_bf16 v[48:63], v[88:91], v[222:225], v[48:63]
	ds_read_b64_tr_b16 v[222:223], v191 offset:0x2400
	ds_read_b64_tr_b16 v[224:225], v191 offset:0x2c00
	v_mfma_f32_32x32x16_bf16 v[48:63], v[92:95], v[234:237], v[48:63]
	ds_read_b64_tr_b16 v[234:235], v191 offset:0x3400
	ds_read_b64_tr_b16 v[236:237], v191 offset:0x3c00
	s_waitcnt lgkmcnt(4)
	v_mfma_f32_32x32x16_bf16 v[32:47], v[80:83], v[214:217], v[32:47]
	ds_read_b64_tr_b16 v[214:215], v191 offset:0x600
	ds_read_b64_tr_b16 v[216:217], v191 offset:0xe00
	v_mfma_f32_32x32x16_bf16 v[32:47], v[84:87], v[218:221], v[32:47]
	ds_read_b64_tr_b16 v[218:219], v191 offset:0x1600
	ds_read_b64_tr_b16 v[220:221], v191 offset:0x1e00
	s_waitcnt lgkmcnt(4)
	v_mfma_f32_32x32x16_bf16 v[32:47], v[88:91], v[222:225], v[32:47]
	ds_read_b64_tr_b16 v[222:223], v191 offset:0x2600
	ds_read_b64_tr_b16 v[224:225], v191 offset:0x2e00
	v_mfma_f32_32x32x16_bf16 v[32:47], v[92:95], v[234:237], v[32:47]
	ds_read_b64_tr_b16 v[234:235], v191 offset:0x3600
	ds_read_b64_tr_b16 v[236:237], v191 offset:0x3e00
	s_waitcnt lgkmcnt(4)
	v_mfma_f32_32x32x16_bf16 v[16:31], v[80:83], v[214:217], v[16:31]
	s_waitcnt vmcnt(4)
	ds_write_b128 v195, v[170:173] offset:49152
	ds_write_b128 v196, v[174:177] offset:49152
	v_mfma_f32_32x32x16_bf16 v[16:31], v[84:87], v[218:221], v[16:31]
	s_waitcnt lgkmcnt(2)
	v_mfma_f32_32x32x16_bf16 v[16:31], v[88:91], v[222:225], v[16:31]
	v_mfma_f32_32x32x16_bf16 v[16:31], v[92:95], v[234:237], v[16:31]
	v_cmp_ge_f32_e32 vcc, s45, v180
	s_cmp_eq_u64 vcc, exec
	v_mov_b32_e32 v170, 1.0
	s_cbranch_scc0 .LBB0_166

; __device__ __forceinline__ int tid_l() { int t = threadIdx.x; asm volatile("" : "+v"(t)); return t; }
; __device__ __forceinline__ int v_st(int k, int c) { const int kk = (k & ~0xC) | ((k & 4) << 1) | ((k & 8) >> 1); return ((kk >> 3) * 4 + (c >> 5)) * 512 + ((kk & 7) * 32 + (c & 31)) * 2; }
; __device__ __forceinline__ int v_rd_base(int lane) { return ((lane & 3) << 3) | (((lane >> 2) & 3) << 6) | (((lane >> 4) & 1) << 5) | (((lane >> 5) & 1) << 8); }
; #define SLOAD_A(k0) do { vs0a = *reinterpret_cast<const bf16x8*>(&Vh[(long)((k0) + sr) * LDK + sc]); vs1a = *reinterpret_cast<const bf16x8*>(&Vh[(long)((k0) + 32 + sr) * LDK + sc]); KLOAD(ks0a, ks1a, k0); } while (0)
; #define SLOAD_B(k0) do { vs0b = *reinterpret_cast<const bf16x8*>(&Vh[(long)((k0) + sr) * LDK + sc]); vs1b = *reinterpret_cast<const bf16x8*>(&Vh[(long)((k0) + 32 + sr) * LDK + sc]); KLOAD(ks0b, ks1b, k0); } while (0)
; template <int ND0, int LDQ, int LDK, int LDO> ...
;   const int tid = tid_l(), wid = tid >> 6, lane = tid & 63, r32 = lane & 31, hi = lane >> 5;
;   char* V_lds = lds; char* K_lds = lds + 2 * SHM_V;
;   float* ws = (float*)(lds + 2 * SHM_V + 2 * SHM_K) + wid * 64; float* li_l = ws; float* al_l = ws + 32;
;   constexpr bool PRE = true;
;   float m_reg = PRE ? 0.f : -1e30f, l_reg = 0; f32x16 o[4] = {}; bf16x8 qr[ND0];
;   const bf16_t* Qw = Qb + (long)(wid * QBLK + r32) * LDQ + hi * 8;
; #pragma unroll
;   for (int d0 = 0; d0 < ND0; ++d0) qr[d0] = *reinterpret_cast<const bf16x8*>(Qw + d0 * 16);
;   const int sr = tid >> 4, sc = (tid & 15) * 8, vst0 = v_st(sr, sc), vst1 = v_st(32 + sr, sc);
;   const int vb0 = (int)(uintptr_t)V_lds + v_rd_base(lane);
;   bf16x8 vs0a, vs1a, ks0a, ks1a = {}, vs0b, vs1b, ks0b, ks1b = {};
;   const int kr = tid >> 3, kcb = kofs + (tid & 7) * 16;
;     ...
;   f32x16 pA0, pA1, pB0, pB1; float mnA, mnB, alA, alB; bf16x8 pa0, pa1, pa2, pa3; const int NT = seq / KVBLK;
;   const char* Kq0 = K_lds + kofs; const char* Kq1 = K_lds + SHM_K + kofs;
;   if (ND0 == 4 && have_pf) { vs0a = pfv0; vs1a = pfv1; ks0a = pfk0; } else { SLOAD_A(0); }
;   asm volatile("s_waitcnt vmcnt(0)" ::: "memory"); SWRITE_A(0); __syncthreads();
;   qkt<ND0>(pA0, pA1, Kq0, qr, r32, hi); PSM(pA0, pA1, mnA, alA);
;   SLOAD_B(KVBLK); if (2 < NT) SLOAD_A(2 * KVBLK);
;   SWAIT(); SWRITE_B(1); __syncthreads();
.LBB0_211:
	v_and_b32_e32 v0, 0xfffff0, v21
	v_lshlrev_b32_e32 v1, 1, v21
	v_and_b32_e32 v4, 0xfffff0, v186
	v_lshlrev_b32_e32 v5, 1, v186
	v_and_or_b32 v0, v1, 8, v0
	v_and_or_b32 v4, v5, 8, v4
	v_lshrrev_b32_e32 v1, 1, v21
	v_lshrrev_b32_e32 v0, 1, v0
	v_lshrrev_b32_e32 v2, 5, v164
	v_and_b32_e32 v3, 3, v21
	v_lshrrev_b32_e32 v4, 1, v4
	v_or_b32_e32 v0, v0, v2
	v_and_or_b32 v1, v1, 4, v3
	v_or_b32_e32 v2, v4, v2
	v_lshlrev_b32_e32 v0, 9, v0
	v_lshlrev_b32_e32 v1, 6, v1
	v_and_b32_e32 v3, 48, v160
	v_lshlrev_b32_e32 v2, 9, v2
	v_or3_b32 v0, v0, v1, v3
	v_or3_b32 v1, v2, v1, v3
	v_add_u32_e32 v194, 0, v1
	v_lshlrev_b32_e32 v1, 4, v22
	v_or_b32_e32 v18, s40, v16
	v_add_u32_e32 v193, 0, v0
	v_lshlrev_b32_e32 v0, 8, v22
	v_and_b32_e32 v1, 0xf0, v1
	v_bitop3_b32 v0, v18, v0, v1 bitop3:0xde
	v_add_u32_e32 v195, 0, v0
	v_lshlrev_b32_e32 v0, 4, v157
	v_lshlrev_b32_e32 v17, 8, v157
	v_and_b32_e32 v19, 0xf0, v0
	s_add_i32 s40, s40, 0
	v_bitop3_b32 v0, v112, v17, v19 bitop3:0xde
	v_xor_b32_e32 v197, s40, v0
	s_waitcnt vmcnt(0)
	s_waitcnt vmcnt(0)
	ds_write_b128 v193, v[64:67]
	ds_write_b128 v194, v[68:71]
	ds_write_b128 v195, v[72:75] offset:32768
	s_waitcnt lgkmcnt(0)
	s_barrier
	ds_read_b128 v[0:3], v197 offset:32768
	ds_read_b128 v[24:27], v197 offset:40960
	v_or_b32_e32 v23, 32, v112
	v_bitop3_b32 v23, v23, v17, v19 bitop3:0xde
	v_xor_b32_e32 v198, s40, v23
	s_waitcnt lgkmcnt(0)
	v_mfma_f32_32x32x16_bf16 v[64:79], v[24:27], v[126:129], 0
	ds_read_b128 v[24:27], v198 offset:32768
	v_or_b32_e32 v23, 64, v112
	v_bitop3_b32 v23, v23, v17, v19 bitop3:0xde
	v_xor_b32_e32 v199, s40, v23
	v_or_b32_e32 v23, 0x60, v112
	v_bitop3_b32 v17, v23, v17, v19 bitop3:0xde
	v_xor_b32_e32 v196, s40, v17
	v_mfma_f32_32x32x16_bf16 v[0:15], v[0:3], v[126:129], 0
	s_waitcnt lgkmcnt(0)
	v_mfma_f32_32x32x16_bf16 v[0:15], v[24:27], v[122:125], v[0:15]
	ds_read_b128 v[24:27], v198 offset:40960
	s_waitcnt lgkmcnt(0)
	v_mfma_f32_32x32x16_bf16 v[64:79], v[24:27], v[122:125], v[64:79]
	ds_read_b128 v[24:27], v199 offset:32768
	s_waitcnt lgkmcnt(0)
	v_mfma_f32_32x32x16_bf16 v[0:15], v[24:27], v[118:121], v[0:15]
	ds_read_b128 v[24:27], v199 offset:40960
	s_waitcnt lgkmcnt(0)
	v_mfma_f32_32x32x16_bf16 v[64:79], v[24:27], v[118:121], v[64:79]
	ds_read_b128 v[24:27], v196 offset:32768
	s_waitcnt lgkmcnt(0)
	v_mfma_f32_32x32x16_bf16 v[0:15], v[24:27], v[114:117], v[0:15]
	ds_read_b128 v[24:27], v196 offset:40960
	s_waitcnt lgkmcnt(0)
	v_mfma_f32_32x32x16_bf16 v[64:79], v[24:27], v[114:117], v[64:79]
	s_nop 8
	v_max_f32_e32 v17, v1, v1
	v_max_f32_e32 v19, v0, v0
	v_max_f32_e32 v17, v19, v17
	v_max3_f32 v17, v17, v2, v3
	v_max3_f32 v17, v17, v4, v5
	v_max3_f32 v17, v17, v6, v7
	v_max3_f32 v17, v17, v8, v9
	v_max3_f32 v17, v17, v10, v11
	v_max3_f32 v17, v17, v12, v13
	v_max3_f32 v17, v17, v14, v15
	v_max3_f32 v17, v17, v64, v65
	v_max3_f32 v17, v17, v66, v67
	v_max3_f32 v17, v17, v68, v69
	v_max3_f32 v17, v17, v70, v71
	v_max3_f32 v17, v17, v72, v73
	v_max3_f32 v17, v17, v74, v75
	v_max3_f32 v17, v17, v76, v77
	v_max3_f32 v17, v17, v78, v79
	v_mov_b32_e32 v19, v17
	s_nop 1
	v_permlane32_swap_b32_e32 v17, v19
	v_max_f32_e32 v19, v19, v19
	v_max_f32_e32 v17, v17, v17
	v_max_f32_e32 v17, v17, v19
	v_cmp_ge_f32_e32 vcc, s45, v17
	s_cmp_eq_u64 vcc, exec
	s_cbranch_scc0 .LBB0_246
	v_mov_b32_e32 v200, 1.0
	v_mov_b32_e32 v191, 0

; #define SBAR() __builtin_amdgcn_sched_barrier(0)
; #define KWRITE(b, src0, src1) do { if constexpr (ND0 == 4) { *(bf16x8*)(K_lds + (b) * SHM_K + KSWZ(kr, kcb)) = src0; } \
;     else { int kc = sc * 2; *(bf16x8*)(K_lds + (b) * SHM_K + KSWZ(sr, kc)) = src0; *(bf16x8*)(K_lds + (b) * SHM_K + KSWZ(32 + sr, kc)) = src1; } } while (0)
; #define SLOAD_B(k0) do { vs0b = *reinterpret_cast<const bf16x8*>(&Vh[(long)((k0) + sr) * LDK + sc]); vs1b = *reinterpret_cast<const bf16x8*>(&Vh[(long)((k0) + 32 + sr) * LDK + sc]); KLOAD(ks0b, ks1b, k0); } while (0)
; #define PSM(P0, P1, MN, AL) do { if constexpr (PRE) partialSM_pre(P0, P1, m_reg, AL, 11.541560327111707f); else partialSM(P0, P1, m_reg, MN, AL, C, thr_raw); } while (0)
; __device__ __forceinline__ void finishSM(f32x16& p0, f32x16& p1, float alpha, float& l_reg, bf16x8& pa0, bf16x8& pa1, bf16x8& pa2, bf16x8& pa3) {
; #pragma unroll
;   for (int r = 0; r < 16; ++r) p1[r] = __builtin_amdgcn_exp2f(p1[r]);
;   float ps = 0;
; #pragma unroll
;   for (int r = 0; r < 16; ++r) ps += p0[r];
; #pragma unroll
;   for (int r = 0; r < 16; ++r) ps += p1[r];
;   { auto rr = __builtin_amdgcn_permlane32_swap(__float_as_uint(ps), __float_as_uint(ps), false, false);
;     ps = __uint_as_float(rr[0]) + __uint_as_float(rr[1]); }
;   l_reg = l_reg * alpha + ps;
;     ...
;   PK4(p0, 0, pa0); PK4(p0, 8, pa1); PK4(p1, 0, pa2); PK4(p1, 8, pa3);
;     ...
; }
; template <int ND0>
; __device__ __forceinline__ void qkt(f32x16& p0, f32x16& p1, const char* Ks, const bf16x8* qr, int r32, int hi) {
;   p0 = f32x16{}; p1 = f32x16{};
; #pragma unroll
;   for (int d0 = 0; d0 < ND0; ++d0) { int cb = (d0 * 16 + hi * 8) * 2;
;     bf16x8 b0 = *reinterpret_cast<const bf16x8*>(Ks + KSWZ(r32, cb));
;     bf16x8 b1 = *reinterpret_cast<const bf16x8*>(Ks + KSWZ(32 + r32, cb));
;     p0 = __builtin_amdgcn_mfma_f32_32x32x16_bf16(b0, qr[d0], p0, 0, 0, 0);
;     p1 = __builtin_amdgcn_mfma_f32_32x32x16_bf16(b1, qr[d0], p1, 0, 0, 0); }
; }
; template <int ND0, int LDQ, int LDK, int LDO> ...
;     ...
;   for (int j = 1; j + 1 < NT; j += 2) {
;     SBAR(); qkt<ND0>(pB0, pB1, Kq1, qr, r32, hi);
;     finishSM(pA0, pA1, alA, l_reg, pa0, pa1, pa2, pa3); SBAR();
;     SLOAD_B((j + 2) * KVBLK); SBAR();
;     pv_d0(o, vb0, pa0, pa1, pa2, pa3); KWRITE(0, ks0a, ks1a); PSM(pB0, pB1, mnB, alB);
.LBB0_214:
	ds_read_b128 v[202:205], v198 offset:49152
	ds_read_b128 v[208:211], v198 offset:57344
	ds_read_b128 v[222:225], v199 offset:49152
	ds_read_b128 v[234:237], v199 offset:57344
	ds_read_b128 v[238:241], v196 offset:49152
	ds_read_b128 v[244:247], v196 offset:57344
	v_exp_f32_e32 v150, v64
	v_add_f32_e32 v64, 0, v176
	s_waitcnt lgkmcnt(6)
	v_mfma_f32_32x32x16_bf16 v[96:111], v[80:83], v[126:129], 0
	v_add_f32_e32 v64, v206, v64
	v_add_f32_e32 v64, v174, v64
	v_add_f32_e32 v64, v177, v64
	v_add_f32_e32 v64, v152, v64
	v_add_f32_e32 v64, v175, v64
	v_add_f32_e32 v64, v151, v64
	v_add_f32_e32 v64, v153, v64
	v_mfma_f32_32x32x16_bf16 v[80:95], v[84:87], v[126:129], 0
	v_add_f32_e32 v64, v147, v64
	v_add_f32_e32 v64, v149, v64
	v_add_f32_e32 v64, v145, v64
	v_add_f32_e32 v64, v148, v64
	v_add_f32_e32 v64, v143, v64
	v_add_f32_e32 v64, v146, v64
	v_add_f32_e32 v64, v142, v64
	s_waitcnt lgkmcnt(4)
	v_mfma_f32_32x32x16_bf16 v[96:111], v[202:205], v[122:125], v[96:111]
	v_add_f32_e32 v64, v144, v64
	v_exp_f32_e32 v207, v68
	v_add_f32_e32 v64, v150, v64
	v_exp_f32_e32 v212, v73
	v_exp_f32_e32 v213, v74
	v_exp_f32_e32 v214, v75
	v_exp_f32_e32 v215, v76
	v_mfma_f32_32x32x16_bf16 v[80:95], v[208:211], v[122:125], v[80:95]
	v_exp_f32_e32 v216, v77
	v_exp_f32_e32 v217, v78
	v_exp_f32_e32 v79, v79
	s_waitcnt lgkmcnt(2)
	v_mfma_f32_32x32x16_bf16 v[96:111], v[222:225], v[118:121], v[96:111]
	v_mfma_f32_32x32x16_bf16 v[80:95], v[234:237], v[118:121], v[80:95]
	s_waitcnt lgkmcnt(0)
	v_mfma_f32_32x32x16_bf16 v[96:111], v[238:241], v[114:117], v[96:111]
	v_exp_f32_e32 v203, v65
	v_exp_f32_e32 v204, v66
	v_exp_f32_e32 v205, v67
	v_add_f32_e32 v64, v203, v64
	v_add_f32_e32 v64, v204, v64
	v_add_f32_e32 v64, v205, v64
	v_mfma_f32_32x32x16_bf16 v[80:95], v[244:247], v[114:117], v[80:95]
	v_exp_f32_e32 v208, v69
	v_exp_f32_e32 v209, v70
	v_exp_f32_e32 v210, v71
	v_exp_f32_e32 v211, v72
	v_add_f32_e32 v64, v207, v64
	v_add_f32_e32 v64, v208, v64
	v_add_f32_e32 v64, v209, v64
	v_add_f32_e32 v64, v210, v64
	v_add_f32_e32 v64, v211, v64
	v_add_f32_e32 v64, v212, v64
	v_add_f32_e32 v64, v213, v64
	v_add_f32_e32 v64, v214, v64
	v_add_f32_e32 v64, v215, v64
	v_add_f32_e32 v64, v216, v64
	v_add_f32_e32 v64, v217, v64
	v_add_f32_e32 v201, v79, v64
	v_mov_b32_e32 v202, v201
	v_cvt_pk_bf16_f32 v64, v176, v206
	v_cvt_pk_bf16_f32 v65, v174, v177
	v_cvt_pk_bf16_f32 v66, v152, v175
	v_cvt_pk_bf16_f32 v67, v151, v153
	v_cvt_pk_bf16_f32 v68, v147, v149
	v_cvt_pk_bf16_f32 v69, v145, v148
	v_cvt_pk_bf16_f32 v70, v143, v146
	v_cvt_pk_bf16_f32 v71, v142, v144
	v_cvt_pk_bf16_f32 v72, v150, v203
	v_cvt_pk_bf16_f32 v73, v204, v205
	v_cvt_pk_bf16_f32 v74, v207, v208
	v_cvt_pk_bf16_f32 v75, v209, v210
	v_cvt_pk_bf16_f32 v76, v211, v212
	v_cvt_pk_bf16_f32 v77, v213, v214
	v_cvt_pk_bf16_f32 v78, v215, v216
	v_cvt_pk_bf16_f32 v79, v217, v79
	v_permlane32_swap_b32_e32 v201, v202
	v_permlane32_swap_b32_e32 v64, v66
	v_permlane32_swap_b32_e32 v65, v67
	v_permlane32_swap_b32_e32 v68, v70
	v_permlane32_swap_b32_e32 v69, v71
	v_permlane32_swap_b32_e32 v72, v74
	v_permlane32_swap_b32_e32 v73, v75
	v_permlane32_swap_b32_e32 v76, v78
	v_permlane32_swap_b32_e32 v77, v79
	v_lshl_add_u64 v[174:175], v[172:173], 0, s[34:35]
	s_mov_b32 s18, 0x13221000
	v_add_co_u32_e32 v142, vcc, s18, v174
	s_mov_b32 s18, 0x13251000
	s_nop 0
	v_addc_co_u32_e32 v143, vcc, 0, v175, vcc
	v_add_co_u32_e32 v146, vcc, s18, v174
	v_lshl_add_u64 v[176:177], v[170:171], 0, s[34:35]
	s_nop 0
	v_addc_co_u32_e32 v147, vcc, 0, v175, vcc
	s_mov_b32 s18, 0x13220000
	v_add_co_u32_e32 v150, vcc, s18, v176
	global_load_dwordx4 v[142:145], v[142:143], off
	global_load_dwordx4 v[146:149], v[146:147], off
	v_addc_co_u32_e32 v151, vcc, 0, v177, vcc
	global_load_dwordx4 v[150:153], v[150:151], off offset:2048
	v_cmp_neq_f32_e32 vcc, 0, v191
	ds_read_b64_tr_b16 v[204:205], v192 offset:0
	ds_read_b64_tr_b16 v[206:207], v192 offset:0x800
	ds_read_b64_tr_b16 v[208:209], v192 offset:0x1000
	ds_read_b64_tr_b16 v[210:211], v192 offset:0x1800
	ds_read_b64_tr_b16 v[212:213], v192 offset:0x2000
	ds_read_b64_tr_b16 v[214:215], v192 offset:0x2800
	ds_read_b64_tr_b16 v[216:217], v192 offset:0x3000
	ds_read_b64_tr_b16 v[218:219], v192 offset:0x3800
	s_cbranch_vccnz .LBB0_230
; #define SBAR() __builtin_amdgcn_sched_barrier(0)
; __device__ __forceinline__ void partialSM_pre(f32x16& p0, f32x16& p1, float& m_ref, float& alpha, const float thr2) {
;     ...
;   float pmax = p0[0];
; #pragma unroll
;   for (int r = 1; r < 16; ++r) pmax = fmaxf(pmax, p0[r]);
; #pragma unroll
;   for (int r = 0; r < 16; ++r) pmax = fmaxf(pmax, p1[r]);
;   { auto rr = __builtin_amdgcn_permlane32_swap(__float_as_uint(pmax), __float_as_uint(pmax), false, false);
;     pmax = fmaxf(__uint_as_float(rr[0]), __uint_as_float(rr[1])); }
;   if (__builtin_expect(__all(pmax <= thr2), 1)) { alpha = 1.f; }
; template <int OFF> __device__ __forceinline__ s16x4 tr_read(int vb) {
;   s16x4 r; asm volatile("ds_read_b64_tr_b16 %0, %1 offset:%2" : "=&v"(r) : "v"(vb), "i"(OFF) : "memory"); return r;
; }
; template <int D0> __device__ __forceinline__ void pv_one(f32x16& od, int vb, bf16x8 pa0, bf16x8 pa1, bf16x8 pa2, bf16x8 pa3) {
;   const s16x4 l0 = tr_read<v_rd_off(D0, 0, 0)>(vb), h0 = tr_read<v_rd_off(D0, 0, 1)>(vb), l1 = tr_read<v_rd_off(D0, 1, 0)>(vb), h1 = tr_read<v_rd_off(D0, 1, 1)>(vb);
;   const s16x4 l2 = tr_read<v_rd_off(D0, 2, 0)>(vb), h2 = tr_read<v_rd_off(D0, 2, 1)>(vb), l3 = tr_read<v_rd_off(D0, 3, 0)>(vb), h3 = tr_read<v_rd_off(D0, 3, 1)>(vb);
;   asm volatile("s_waitcnt lgkmcnt(0)" ::: "memory"); SBAR();
;     ...
;   od = __builtin_amdgcn_mfma_f32_32x32x16_bf16(pa0, PK(l0, h0), od, 0, 0, 0);
;   od = __builtin_amdgcn_mfma_f32_32x32x16_bf16(pa1, PK(l1, h1), od, 0, 0, 0);
;   od = __builtin_amdgcn_mfma_f32_32x32x16_bf16(pa2, PK(l2, h2), od, 0, 0, 0);
;   od = __builtin_amdgcn_mfma_f32_32x32x16_bf16(pa3, PK(l3, h3), od, 0, 0, 0);
;     ...
; }
; __device__ __forceinline__ void pv_d0(f32x16* o, int vb, bf16x8 pa0, bf16x8 pa1, bf16x8 pa2, bf16x8 pa3) {
;   pv_one<0>(o[0], vb, pa0, pa1, pa2, pa3); pv_one<1>(o[1], vb, pa0, pa1, pa2, pa3); pv_one<2>(o[2], vb, pa0, pa1, pa2, pa3); pv_one<3>(o[3], vb, pa0, pa1, pa2, pa3);
; }
.LBB0_215:
	v_max_f32_e32 v252, v97, v97
	v_max_f32_e32 v253, v96, v96
	v_max_f32_e32 v252, v253, v252
	v_max3_f32 v252, v252, v98, v99
	v_max3_f32 v252, v252, v100, v101
	v_max3_f32 v252, v252, v102, v103
	v_max3_f32 v252, v252, v104, v105
	v_max3_f32 v252, v252, v106, v107
	v_max3_f32 v252, v252, v108, v109
	v_max3_f32 v252, v252, v110, v111
	v_max3_f32 v252, v252, v80, v81
	v_max3_f32 v252, v252, v82, v83
	v_max3_f32 v252, v252, v84, v85
	v_max3_f32 v252, v252, v86, v87
	v_max3_f32 v252, v252, v88, v89
	v_max3_f32 v252, v252, v90, v91
	v_max3_f32 v252, v252, v92, v93
	v_max3_f32 v252, v252, v94, v95
	v_mov_b32_e32 v253, v252
	s_nop 1
	v_permlane32_swap_b32_e32 v252, v253
	v_max_f32_e32 v253, v253, v253
	v_max_f32_e32 v252, v252, v252
	v_max_f32_e32 v252, v252, v253
	s_waitcnt lgkmcnt(4)
	v_mfma_f32_32x32x16_bf16 v[0:15], v[64:67], v[204:207], v[0:15]
	ds_read_b64_tr_b16 v[204:205], v192 offset:0x200
	ds_read_b64_tr_b16 v[206:207], v192 offset:0xa00
	v_mfma_f32_32x32x16_bf16 v[0:15], v[68:71], v[208:211], v[0:15]
	ds_read_b64_tr_b16 v[208:209], v192 offset:0x1200
	ds_read_b64_tr_b16 v[210:211], v192 offset:0x1a00
	s_waitcnt lgkmcnt(4)
	v_mfma_f32_32x32x16_bf16 v[0:15], v[72:75], v[212:215], v[0:15]
	ds_read_b64_tr_b16 v[212:213], v192 offset:0x2200
	ds_read_b64_tr_b16 v[214:215], v192 offset:0x2a00
	v_mfma_f32_32x32x16_bf16 v[0:15], v[76:79], v[216:219], v[0:15]
	ds_read_b64_tr_b16 v[216:217], v192 offset:0x3200
	ds_read_b64_tr_b16 v[218:219], v192 offset:0x3a00
	s_waitcnt lgkmcnt(4)
	v_mfma_f32_32x32x16_bf16 v[48:63], v[64:67], v[204:207], v[48:63]
	ds_read_b64_tr_b16 v[204:205], v192 offset:0x400
	ds_read_b64_tr_b16 v[206:207], v192 offset:0xc00
	v_mfma_f32_32x32x16_bf16 v[48:63], v[68:71], v[208:211], v[48:63]
	ds_read_b64_tr_b16 v[208:209], v192 offset:0x1400
	ds_read_b64_tr_b16 v[210:211], v192 offset:0x1c00
	s_waitcnt lgkmcnt(4)
	v_mfma_f32_32x32x16_bf16 v[48:63], v[72:75], v[212:215], v[48:63]
	ds_read_b64_tr_b16 v[212:213], v192 offset:0x2400
	ds_read_b64_tr_b16 v[214:215], v192 offset:0x2c00
	v_mfma_f32_32x32x16_bf16 v[48:63], v[76:79], v[216:219], v[48:63]
	ds_read_b64_tr_b16 v[216:217], v192 offset:0x3400
	ds_read_b64_tr_b16 v[218:219], v192 offset:0x3c00
	s_waitcnt lgkmcnt(4)
	v_mfma_f32_32x32x16_bf16 v[32:47], v[64:67], v[204:207], v[32:47]
	ds_read_b64_tr_b16 v[204:205], v192 offset:0x600
	ds_read_b64_tr_b16 v[206:207], v192 offset:0xe00
	v_mfma_f32_32x32x16_bf16 v[32:47], v[68:71], v[208:211], v[32:47]
	ds_read_b64_tr_b16 v[208:209], v192 offset:0x1600
	ds_read_b64_tr_b16 v[210:211], v192 offset:0x1e00
	s_waitcnt lgkmcnt(4)
	v_mfma_f32_32x32x16_bf16 v[32:47], v[72:75], v[212:215], v[32:47]
	ds_read_b64_tr_b16 v[212:213], v192 offset:0x2600
	ds_read_b64_tr_b16 v[214:215], v192 offset:0x2e00
	v_mfma_f32_32x32x16_bf16 v[32:47], v[76:79], v[216:219], v[32:47]
	ds_read_b64_tr_b16 v[216:217], v192 offset:0x3600
	ds_read_b64_tr_b16 v[218:219], v192 offset:0x3e00
	s_waitcnt lgkmcnt(4)
	v_mfma_f32_32x32x16_bf16 v[16:31], v[64:67], v[204:207], v[16:31]
	s_waitcnt vmcnt(3)
	ds_write_b128 v195, v[138:141] offset:32768
	v_mfma_f32_32x32x16_bf16 v[16:31], v[68:71], v[208:211], v[16:31]
	s_waitcnt lgkmcnt(1)
	v_mfma_f32_32x32x16_bf16 v[16:31], v[72:75], v[212:215], v[16:31]
	v_mfma_f32_32x32x16_bf16 v[16:31], v[76:79], v[216:219], v[16:31]
	v_cmp_ge_f32_e32 vcc, s45, v252
	s_cmp_eq_u64 vcc, exec
	v_mov_b32_e32 v203, 1.0
	s_cbranch_scc0 .LBB0_231

; #define SBAR() __builtin_amdgcn_sched_barrier(0)
; #define KWRITE(b, src0, src1) do { if constexpr (ND0 == 4) { *(bf16x8*)(K_lds + (b) * SHM_K + KSWZ(kr, kcb)) = src0; } \
;     else { int kc = sc * 2; *(bf16x8*)(K_lds + (b) * SHM_K + KSWZ(sr, kc)) = src0; *(bf16x8*)(K_lds + (b) * SHM_K + KSWZ(32 + sr, kc)) = src1; } } while (0)
; #define SLOAD_A(k0) do { vs0a = *reinterpret_cast<const bf16x8*>(&Vh[(long)((k0) + sr) * LDK + sc]); vs1a = *reinterpret_cast<const bf16x8*>(&Vh[(long)((k0) + 32 + sr) * LDK + sc]); KLOAD(ks0a, ks1a, k0); } while (0)
; #define PSM(P0, P1, MN, AL) do { if constexpr (PRE) partialSM_pre(P0, P1, m_reg, AL, 11.541560327111707f); else partialSM(P0, P1, m_reg, MN, AL, C, thr_raw); } while (0)
; __device__ __forceinline__ void finishSM(f32x16& p0, f32x16& p1, float alpha, float& l_reg, bf16x8& pa0, bf16x8& pa1, bf16x8& pa2, bf16x8& pa3) {
; #pragma unroll
;   for (int r = 0; r < 16; ++r) p1[r] = __builtin_amdgcn_exp2f(p1[r]);
;   float ps = 0;
; #pragma unroll
;   for (int r = 0; r < 16; ++r) ps += p0[r];
; #pragma unroll
;   for (int r = 0; r < 16; ++r) ps += p1[r];
;   { auto rr = __builtin_amdgcn_permlane32_swap(__float_as_uint(ps), __float_as_uint(ps), false, false);
;     ps = __uint_as_float(rr[0]) + __uint_as_float(rr[1]); }
;   l_reg = l_reg * alpha + ps;
;     ...
;   PK4(p0, 0, pa0); PK4(p0, 8, pa1); PK4(p1, 0, pa2); PK4(p1, 8, pa3);
;     ...
; }
; template <int ND0>
; __device__ __forceinline__ void qkt(f32x16& p0, f32x16& p1, const char* Ks, const bf16x8* qr, int r32, int hi) {
;   p0 = f32x16{}; p1 = f32x16{};
; #pragma unroll
;   for (int d0 = 0; d0 < ND0; ++d0) { int cb = (d0 * 16 + hi * 8) * 2;
;     bf16x8 b0 = *reinterpret_cast<const bf16x8*>(Ks + KSWZ(r32, cb));
;     bf16x8 b1 = *reinterpret_cast<const bf16x8*>(Ks + KSWZ(32 + r32, cb));
;     p0 = __builtin_amdgcn_mfma_f32_32x32x16_bf16(b0, qr[d0], p0, 0, 0, 0);
;     p1 = __builtin_amdgcn_mfma_f32_32x32x16_bf16(b1, qr[d0], p1, 0, 0, 0); }
; }
; template <int ND0, int LDQ, int LDK, int LDO> ...
;     ...
;     SBAR(); qkt<ND0>(pA0, pA1, Kq0, qr, r32, hi);
;     finishSM(pB0, pB1, alB, l_reg, pa0, pa1, pa2, pa3); SBAR();
;     if (j + 3 < NT) SLOAD_A((j + 3) * KVBLK); SBAR();
;     pv_d0(o, vb0 + (int)SHM_V, pa0, pa1, pa2, pa3); KWRITE(1, ks0b, ks1b); PSM(pA0, pA1, mnA, alA);
.LBB0_220:
	ds_read_b128 v[64:67], v197 offset:32768
	ds_read_b128 v[68:71], v197 offset:40960
	ds_read_b128 v[222:225], v198 offset:32768
	ds_read_b128 v[244:247], v198 offset:40960
	ds_read_b128 v[130:133], v199 offset:32768
	ds_read_b128 v[134:137], v199 offset:40960
	ds_read_b128 v[138:141], v196 offset:32768
	v_exp_f32_e32 v226, v84
	v_exp_f32_e32 v227, v85
	s_waitcnt lgkmcnt(5)
	v_mfma_f32_32x32x16_bf16 v[96:111], v[64:67], v[126:129], 0
	v_exp_f32_e32 v234, v86
	v_exp_f32_e32 v235, v87
	v_exp_f32_e32 v236, v88
	v_exp_f32_e32 v237, v89
	v_exp_f32_e32 v238, v90
	v_exp_f32_e32 v239, v91
	v_exp_f32_e32 v240, v92
	v_mfma_f32_32x32x16_bf16 v[64:79], v[68:71], v[126:129], 0
	v_exp_f32_e32 v241, v93
	v_exp_f32_e32 v95, v95
	s_waitcnt lgkmcnt(3)
	v_mfma_f32_32x32x16_bf16 v[96:111], v[222:225], v[122:125], v[96:111]
	v_mfma_f32_32x32x16_bf16 v[64:79], v[244:247], v[122:125], v[64:79]
	ds_read_b128 v[244:247], v196 offset:40960
	s_waitcnt lgkmcnt(2)
	v_mfma_f32_32x32x16_bf16 v[96:111], v[130:133], v[118:121], v[96:111]
	v_mfma_f32_32x32x16_bf16 v[64:79], v[134:137], v[118:121], v[64:79]
	s_waitcnt lgkmcnt(0)
	v_mfma_f32_32x32x16_bf16 v[96:111], v[138:141], v[114:117], v[96:111]
	v_exp_f32_e32 v222, v80
	v_add_f32_e32 v80, 0, v219
	v_add_f32_e32 v80, v221, v80
	v_add_f32_e32 v80, v217, v80
	v_add_f32_e32 v80, v220, v80
	v_add_f32_e32 v80, v215, v80
	v_add_f32_e32 v80, v218, v80
	v_add_f32_e32 v80, v214, v80
	v_add_f32_e32 v80, v216, v80
	v_add_f32_e32 v80, v211, v80
	v_add_f32_e32 v80, v213, v80
	v_add_f32_e32 v80, v209, v80
	v_add_f32_e32 v80, v212, v80
	v_add_f32_e32 v80, v207, v80
	v_exp_f32_e32 v223, v81
	v_add_f32_e32 v80, v210, v80
	v_exp_f32_e32 v224, v82
	v_add_f32_e32 v80, v206, v80
	v_exp_f32_e32 v225, v83
	v_add_f32_e32 v80, v208, v80
	v_add_f32_e32 v80, v222, v80
	v_add_f32_e32 v80, v223, v80
	v_add_f32_e32 v80, v224, v80
	v_add_f32_e32 v80, v225, v80
	v_add_f32_e32 v80, v226, v80
	v_add_f32_e32 v80, v227, v80
	v_add_f32_e32 v80, v234, v80
	v_add_f32_e32 v80, v235, v80
	v_add_f32_e32 v80, v236, v80
	v_add_f32_e32 v80, v237, v80
	v_mfma_f32_32x32x16_bf16 v[64:79], v[244:247], v[114:117], v[64:79]
	v_exp_f32_e32 v244, v94
	v_add_f32_e32 v80, v238, v80
	v_add_f32_e32 v80, v239, v80
	v_add_f32_e32 v80, v240, v80
	v_add_f32_e32 v80, v241, v80
	v_add_f32_e32 v80, v244, v80
	v_add_f32_e32 v204, v95, v80
	v_mov_b32_e32 v205, v204
	v_cvt_pk_bf16_f32 v80, v219, v221
	v_cvt_pk_bf16_f32 v81, v217, v220
	v_cvt_pk_bf16_f32 v82, v215, v218
	v_cvt_pk_bf16_f32 v83, v214, v216
	v_cvt_pk_bf16_f32 v84, v211, v213
	v_cvt_pk_bf16_f32 v85, v209, v212
	v_cvt_pk_bf16_f32 v86, v207, v210
	v_cvt_pk_bf16_f32 v87, v206, v208
	v_cvt_pk_bf16_f32 v88, v222, v223
	v_cvt_pk_bf16_f32 v89, v224, v225
	v_cvt_pk_bf16_f32 v90, v226, v227
	v_cvt_pk_bf16_f32 v91, v234, v235
	v_cvt_pk_bf16_f32 v92, v236, v237
	v_cvt_pk_bf16_f32 v93, v238, v239
	v_cvt_pk_bf16_f32 v94, v240, v241
	v_cvt_pk_bf16_f32 v95, v244, v95
	v_permlane32_swap_b32_e32 v204, v205
	v_permlane32_swap_b32_e32 v80, v82
	v_permlane32_swap_b32_e32 v81, v83
	v_permlane32_swap_b32_e32 v84, v86
	v_permlane32_swap_b32_e32 v85, v87
	v_permlane32_swap_b32_e32 v88, v90
	v_permlane32_swap_b32_e32 v89, v91
	v_permlane32_swap_b32_e32 v92, v94
	v_permlane32_swap_b32_e32 v93, v95
	s_cmp_ge_u32 s40, s39
	s_cselect_b64 s[18:19], -1, 0
	s_and_b64 vcc, exec, s[18:19]
	s_cbranch_vccnz .Ldiff_pf_skip
	v_add_co_u32_e32 v130, vcc, 0x13281000, v174
	s_nop 1
	v_addc_co_u32_e32 v131, vcc, 0, v175, vcc
	v_add_co_u32_e32 v134, vcc, 0x132b1000, v174
	s_nop 1
	v_addc_co_u32_e32 v135, vcc, 0, v175, vcc
	v_add_co_u32_e32 v138, vcc, 0x13280000, v176
	global_load_dwordx4 v[130:133], v[130:131], off
	global_load_dwordx4 v[134:137], v[134:135], off
	v_addc_co_u32_e32 v139, vcc, 0, v177, vcc
	global_load_dwordx4 v[138:141], v[138:139], off offset:2048

; #define SBAR() __builtin_amdgcn_sched_barrier(0)
; __device__ __forceinline__ void partialSM_pre(f32x16& p0, f32x16& p1, float& m_ref, float& alpha, const float thr2) {
;     ...
;   float pmax = p0[0];
; #pragma unroll
;   for (int r = 1; r < 16; ++r) pmax = fmaxf(pmax, p0[r]);
; #pragma unroll
;   for (int r = 0; r < 16; ++r) pmax = fmaxf(pmax, p1[r]);
;   { auto rr = __builtin_amdgcn_permlane32_swap(__float_as_uint(pmax), __float_as_uint(pmax), false, false);
;     pmax = fmaxf(__uint_as_float(rr[0]), __uint_as_float(rr[1])); }
;   if (__builtin_expect(__all(pmax <= thr2), 1)) { alpha = 1.f; }
; template <int OFF> __device__ __forceinline__ s16x4 tr_read(int vb) {
;   s16x4 r; asm volatile("ds_read_b64_tr_b16 %0, %1 offset:%2" : "=&v"(r) : "v"(vb), "i"(OFF) : "memory"); return r;
; }
; template <int D0> __device__ __forceinline__ void pv_one(f32x16& od, int vb, bf16x8 pa0, bf16x8 pa1, bf16x8 pa2, bf16x8 pa3) {
;   const s16x4 l0 = tr_read<v_rd_off(D0, 0, 0)>(vb), h0 = tr_read<v_rd_off(D0, 0, 1)>(vb), l1 = tr_read<v_rd_off(D0, 1, 0)>(vb), h1 = tr_read<v_rd_off(D0, 1, 1)>(vb);
;   const s16x4 l2 = tr_read<v_rd_off(D0, 2, 0)>(vb), h2 = tr_read<v_rd_off(D0, 2, 1)>(vb), l3 = tr_read<v_rd_off(D0, 3, 0)>(vb), h3 = tr_read<v_rd_off(D0, 3, 1)>(vb);
;   asm volatile("s_waitcnt lgkmcnt(0)" ::: "memory"); SBAR();
;     ...
;   od = __builtin_amdgcn_mfma_f32_32x32x16_bf16(pa0, PK(l0, h0), od, 0, 0, 0);
;   od = __builtin_amdgcn_mfma_f32_32x32x16_bf16(pa1, PK(l1, h1), od, 0, 0, 0);
;   od = __builtin_amdgcn_mfma_f32_32x32x16_bf16(pa2, PK(l2, h2), od, 0, 0, 0);
;   od = __builtin_amdgcn_mfma_f32_32x32x16_bf16(pa3, PK(l3, h3), od, 0, 0, 0);
;     ...
; }
; __device__ __forceinline__ void pv_d0(f32x16* o, int vb, bf16x8 pa0, bf16x8 pa1, bf16x8 pa2, bf16x8 pa3) {
;   pv_one<0>(o[0], vb, pa0, pa1, pa2, pa3); pv_one<1>(o[1], vb, pa0, pa1, pa2, pa3); pv_one<2>(o[2], vb, pa0, pa1, pa2, pa3); pv_one<3>(o[3], vb, pa0, pa1, pa2, pa3);
; }
.LBB0_223:
	v_max_f32_e32 v252, v97, v97
	v_max_f32_e32 v253, v96, v96
	v_max_f32_e32 v252, v253, v252
	v_max3_f32 v252, v252, v98, v99
	v_max3_f32 v252, v252, v100, v101
	v_max3_f32 v252, v252, v102, v103
	v_max3_f32 v252, v252, v104, v105
	v_max3_f32 v252, v252, v106, v107
	v_max3_f32 v252, v252, v108, v109
	v_max3_f32 v252, v252, v110, v111
	v_max3_f32 v252, v252, v64, v65
	v_max3_f32 v252, v252, v66, v67
	v_max3_f32 v252, v252, v68, v69
	v_max3_f32 v252, v252, v70, v71
	v_max3_f32 v252, v252, v72, v73
	v_max3_f32 v252, v252, v74, v75
	v_max3_f32 v252, v252, v76, v77
	v_max3_f32 v252, v252, v78, v79
	v_mov_b32_e32 v253, v252
	s_nop 1
	v_permlane32_swap_b32_e32 v252, v253
	v_max_f32_e32 v253, v253, v253
	v_max_f32_e32 v252, v252, v252
	v_max_f32_e32 v252, v252, v253
	s_waitcnt lgkmcnt(4)
	v_mfma_f32_32x32x16_bf16 v[0:15], v[80:83], v[174:177], v[0:15]
	ds_read_b64_tr_b16 v[174:175], v190 offset:0x200
	ds_read_b64_tr_b16 v[176:177], v190 offset:0xa00
	v_mfma_f32_32x32x16_bf16 v[0:15], v[84:87], v[206:209], v[0:15]
	ds_read_b64_tr_b16 v[206:207], v190 offset:0x1200
	ds_read_b64_tr_b16 v[208:209], v190 offset:0x1a00
	s_waitcnt lgkmcnt(4)
	v_mfma_f32_32x32x16_bf16 v[0:15], v[88:91], v[210:213], v[0:15]
	ds_read_b64_tr_b16 v[210:211], v190 offset:0x2200
	ds_read_b64_tr_b16 v[212:213], v190 offset:0x2a00
	v_mfma_f32_32x32x16_bf16 v[0:15], v[92:95], v[214:217], v[0:15]
	ds_read_b64_tr_b16 v[214:215], v190 offset:0x3200
	ds_read_b64_tr_b16 v[216:217], v190 offset:0x3a00
	s_waitcnt lgkmcnt(4)
	v_mfma_f32_32x32x16_bf16 v[48:63], v[80:83], v[174:177], v[48:63]
	ds_read_b64_tr_b16 v[174:175], v190 offset:0x400
	ds_read_b64_tr_b16 v[176:177], v190 offset:0xc00
	v_mfma_f32_32x32x16_bf16 v[48:63], v[84:87], v[206:209], v[48:63]
	ds_read_b64_tr_b16 v[206:207], v190 offset:0x1400
	ds_read_b64_tr_b16 v[208:209], v190 offset:0x1c00
	s_waitcnt lgkmcnt(4)
	v_mfma_f32_32x32x16_bf16 v[48:63], v[88:91], v[210:213], v[48:63]
	ds_read_b64_tr_b16 v[210:211], v190 offset:0x2400
	ds_read_b64_tr_b16 v[212:213], v190 offset:0x2c00
	v_mfma_f32_32x32x16_bf16 v[48:63], v[92:95], v[214:217], v[48:63]
	ds_read_b64_tr_b16 v[214:215], v190 offset:0x3400
	ds_read_b64_tr_b16 v[216:217], v190 offset:0x3c00
	s_waitcnt lgkmcnt(4)
	v_mfma_f32_32x32x16_bf16 v[32:47], v[80:83], v[174:177], v[32:47]
	ds_read_b64_tr_b16 v[174:175], v190 offset:0x600
	ds_read_b64_tr_b16 v[176:177], v190 offset:0xe00
	v_mfma_f32_32x32x16_bf16 v[32:47], v[84:87], v[206:209], v[32:47]
	ds_read_b64_tr_b16 v[206:207], v190 offset:0x1600
	ds_read_b64_tr_b16 v[208:209], v190 offset:0x1e00
	s_waitcnt lgkmcnt(4)
	v_mfma_f32_32x32x16_bf16 v[32:47], v[88:91], v[210:213], v[32:47]
	ds_read_b64_tr_b16 v[210:211], v190 offset:0x2600
	ds_read_b64_tr_b16 v[212:213], v190 offset:0x2e00
	v_mfma_f32_32x32x16_bf16 v[32:47], v[92:95], v[214:217], v[32:47]
	ds_read_b64_tr_b16 v[214:215], v190 offset:0x3600
	ds_read_b64_tr_b16 v[216:217], v190 offset:0x3e00
	s_waitcnt lgkmcnt(4)
	v_mfma_f32_32x32x16_bf16 v[16:31], v[80:83], v[174:177], v[16:31]
	s_waitcnt vmcnt(3)
	ds_write_b128 v195, v[150:153] offset:49152
	v_mfma_f32_32x32x16_bf16 v[16:31], v[84:87], v[206:209], v[16:31]
	s_waitcnt lgkmcnt(1)
	v_mfma_f32_32x32x16_bf16 v[16:31], v[88:91], v[210:213], v[16:31]
	v_mfma_f32_32x32x16_bf16 v[16:31], v[92:95], v[214:217], v[16:31]
	v_cmp_ge_f32_e32 vcc, s45, v252
	s_cmp_eq_u64 vcc, exec
	v_mov_b32_e32 v150, 1.0
	s_cbranch_scc0 .LBB0_233
